# differential attention loops: Q pre-scaled by 0.125*log2e (re-rounded bf16), 64 v_fma per 2 tiles removed, m=0
# speedup vs baseline: 1.0350x; 1.0184x over previous
; DI int ltid() { int t; asm volatile("v_mov_b32 %0, %1" : "=v"(t) : "v"(threadIdx.x)); return t; }
; #define A_LOAD(t, rk, rv) do { const size_t kb_ = (size_t)(t) * 64; \
;     _Pragma("unroll") for (int s = 0; s < NK; ++s) _Pragma("unroll") for (int i = 0; i < KI; ++i) rk[s][i] = *(const u32x4*)(J.k[s] + (kb_ + ksrow + 32 * i) * J.ldk + ksch * 8); \
;     _Pragma("unroll") for (int i = 0; i < VI; ++i) rv[i] = *(const u32x4*)(J.v + (kb_ + vkey0 + (STN / VCH) * i) * J.ldv + vc8); } while (0)
; template <int DV, int NK, int MODE, bool FIXM, int GRP>
; DI void attn_job(char* lds_wg, const AttnJob& J) {
;     ...
;   const int tid_wg = ltid(), tid = tid_wg & (AT - 1), lane = tid & 63, wid = __builtin_amdgcn_readfirstlane(tid >> 6), r = lane & 31, h = lane >> 5;
;   constexpr bool SHR = FIXM || MODE == AM_SWA;
;   constexpr int STN = SHR ? NTHREADS : AT;
;   char* lds = lds_wg + (SHR ? 0 : GRP * 65536);
;   const int st_ = SHR ? tid_wg : tid;
;   const int kstream = (NK == 2) ? (wid & 1) : 0;
;   bf16x8 qf[4];
;   const bf16_t* qrow = J.q + (size_t)r * UW + 8 * h;
; #pragma unroll
;   for (int ds = 0; ds < 4; ++ds) qf[ds] = *(const bf16x8*)(qrow + 16 * ds);
;   f32x16 O[NDV];
; #pragma unroll
;   for (int d = 0; d < NDV; ++d)
; #pragma unroll
;     for (int i = 0; i < 16; ++i) O[d][i] = 0.f;
;   float m = J.m_init, l = (h == 0) ? J.l_init : 0.f;
;   f32x16 Osum;
; #pragma unroll
;   for (int i = 0; i < 16; ++i) Osum[i] = 0.f;
;   const bf16x8 ones = {0x3F80, 0x3F80, 0x3F80, 0x3F80, 0x3F80, 0x3F80, 0x3F80, 0x3F80};
;   constexpr int KI = 512 / STN;
;   const int ksrow = st_ >> 3, ksch = st_ & 7;
;   const int kpi = (ksrow & ~12) | ((ksrow & 4) << 1) | ((ksrow & 8) >> 1);
;   const int ksoff = kpi * 128 + ((ksch ^ ((kpi >> 1) & 7)) << 4);
;   constexpr int VCH = DV / 8;
;   constexpr int VI = (64 * VCH) / STN;
;   const int vkey0 = st_ / VCH, vc8 = (st_ % VCH) * 8;
;   u32x4 rk0[NK][KI], rv0[VI], rk1[NK][KI], rv1[VI];
;     ...
;   const int nt = J.tile_hi - J.tile_lo;
;   constexpr bool DEEP2 = FIXM || MODE != AM_DIFF;
;   constexpr bool ONESET = FIXM;
;   A_LOAD(J.tile_lo, rk0, rv0); A_WRITE(0, rk0, rv0); if (ONESET) A_LOAD(J.tile_lo + 1, rk0, rv0); else if (DEEP2) A_LOAD(J.tile_lo + 1, rk1, rv1); __syncthreads();
.LBB0_320:
	s_andn2_b64 vcc, exec, s[70:71]
	s_cbranch_vccnz .LBB0_292
	s_add_u32 s70, s68, 0xa00
	s_addc_u32 s71, s69, 0
	s_add_u32 s72, s68, 0xa80
	s_addc_u32 s73, s69, 0
	s_and_b64 vcc, exec, s[4:5]
	s_mov_b64 s[4:5], -1
	s_cbranch_vccnz .LBB0_338
	v_mov_b32 v30, v212
	v_mov_b64_e32 v[2:3], s[68:69]
	v_ashrrev_i32_e32 v0, 31, v30
	v_lshrrev_b32_e32 v0, 28, v0
	v_add_u32_e32 v0, v30, v0
	v_ashrrev_i32_e32 v32, 4, v0
	v_and_b32_e32 v0, -16, v0
	v_sub_u32_e32 v33, v30, v0
	v_lshlrev_b32_e32 v10, 3, v33
	v_ashrrev_i32_e32 v11, 31, v10
	v_lshlrev_b64 v[20:21], 1, v[10:11]
	v_lshl_add_u64 v[10:11], s[68:69], 0, v[20:21]
	v_ashrrev_i32_e32 v31, 3, v30
	v_lshlrev_b32_e32 v34, 4, v30
	v_mad_i64_i32 v[22:23], s[4:5], v32, s13, v[10:11]
	v_mad_i64_i32 v[2:3], s[4:5], v31, s13, v[2:3]
	v_and_b32_e32 v18, 0x70, v34
	v_mov_b32_e32 v19, v1
	v_add_co_u32_e32 v14, vcc, s22, v22
	v_lshl_add_u64 v[6:7], v[2:3], 0, v[18:19]
	s_nop 0
	v_addc_co_u32_e32 v15, vcc, 0, v23, vcc
	global_load_dwordx4 v[2:5], v[6:7], off offset:2560
	s_nop 0
	global_load_dwordx4 v[6:9], v[6:7], off offset:2688
	s_nop 0
	global_load_dwordx4 v[10:13], v[22:23], off offset:3584
	s_nop 0
	global_load_dwordx4 v[14:17], v[14:15], off offset:3584
	v_mov_b64_e32 v[24:25], s[96:97]
	v_and_b32_e32 v146, 31, v30
	v_bfe_u32 v130, v30, 5, 1
	v_lshlrev_b32_e32 v28, 1, v31
	v_lshrrev_b32_e32 v29, 1, v31
	v_mad_u64_u32 v[24:25], s[4:5], v146, s13, v[24:25]
	v_lshlrev_b32_e32 v0, 4, v130
	v_and_b32_e32 v36, -13, v31
	v_mad_i64_i32 v[26:27], s[4:5], v31, s13, v[166:167]
	v_and_b32_e32 v37, 8, v28
	v_and_b32_e32 v38, 4, v29
	v_lshl_add_u64 v[24:25], v[24:25], 0, v[0:1]
	v_lshl_add_u64 v[28:29], s[70:71], 0, v[26:27]
	v_lshl_add_u64 v[26:27], s[72:73], 0, v[26:27]
	v_or3_b32 v36, v37, v36, v38
	global_load_dwordx4 v[98:101], v[24:25], off offset:1536
	global_load_dwordx4 v[102:105], v[24:25], off offset:1568
	global_load_dwordx4 v[106:109], v[24:25], off offset:1600
	global_load_dwordx4 v[110:113], v[24:25], off offset:1632
	v_lshl_add_u64 v[24:25], v[28:29], 0, v[18:19]
	v_lshl_add_u64 v[18:19], v[26:27], 0, v[18:19]
	v_lshrrev_b32_e32 v27, 1, v36
	v_lshlrev_b32_e32 v26, 7, v36
	v_lshrrev_b32_e32 v29, 1, v32
	v_add_u32_e32 v36, 32, v32
	global_load_dwordx4 v[114:117], v[24:25], off
	global_load_dwordx4 v[118:121], v[18:19], off
	v_xor_b32_e32 v18, v27, v30
	v_ashrrev_i32_e32 v19, 2, v33
	v_and_b32_e32 v25, 0x7ffffc, v29
	v_lshrrev_b32_e32 v27, 1, v36
	v_lshlrev_b32_e32 v18, 4, v18
	v_add_lshl_u32 v140, v25, v19, 9
	v_and_b32_e32 v25, 0x7ffffc, v27
	v_and_or_b32 v141, v18, s12, v26
	v_add_co_u32_e32 v18, vcc, s34, v22
	v_add_lshl_u32 v143, v25, v19, 9
	s_nop 0
	v_addc_co_u32_e32 v19, vcc, 0, v23, vcc
	v_add_co_u32_e32 v22, vcc, s20, v22
	v_lshlrev_b32_e32 v24, 4, v33
	s_nop 0
	v_addc_co_u32_e32 v23, vcc, 0, v23, vcc
	global_load_dwordx4 v[122:125], v[18:19], off offset:3584
	global_load_dwordx4 v[126:129], v[22:23], off offset:3584
	v_lshlrev_b32_e32 v28, 6, v32
	v_and_b32_e32 v24, 48, v24
	v_and_or_b32 v142, v28, s6, v24
	v_or_b32_e32 v24, v142, v140
	v_or_b32_e32 v25, v142, v143
	v_lshrrev_b32_e32 v35, 5, v30
	v_readfirstlane_b32 s38, v30
	s_lshl_b32 s4, s38, 7
	s_and_b32 s4, s4, 0x2000
	v_readlane_b32 s44, v254, 33
	v_readlane_b32 s48, v254, 37
	v_readlane_b32 s49, v254, 38
	v_mov_b32_e32 v150, 0
	s_mov_b32 s41, 0
	s_lshr_b32 s39, s38, 6
	v_mov_b32_e32 v18, 0
	v_mov_b32_e32 v19, v150
	v_mov_b32_e32 v22, v150
	v_mov_b32_e32 v23, v150
	v_mov_b32_e32 v26, v150
	v_mov_b32_e32 v27, v150
	s_waitcnt vmcnt(11)
	ds_write_b128 v141, v[2:5]
	s_waitcnt vmcnt(10)
	ds_write_b128 v141, v[6:9] offset:8192
	s_waitcnt vmcnt(9)
	ds_write_b128 v24, v[10:13] offset:16384
	s_waitcnt vmcnt(8)
	ds_write_b128 v25, v[14:17] offset:16384
	v_lshlrev_b32_e32 v4, 2, v30
	v_and_b32_e32 v5, 16, v30
	v_and_or_b32 v4, v4, 12, v5
	v_lshlrev_b32_e32 v2, 11, v130
	v_and_b32_e32 v3, 0xc0, v34
	v_lshlrev_b32_e32 v4, 1, v4
	v_or3_b32 v144, v2, v3, v4
	v_bfe_u32 v2, v30, 1, 3
	v_bitop3_b32 v3, v35, v2, 1 bitop3:0x6c
	v_lshlrev_b32_e32 v7, 4, v3
	v_bitop3_b32 v3, v130, v2, 2 bitop3:0x36
	v_lshlrev_b32_e32 v8, 4, v3
	v_bitop3_b32 v3, v130, v2, 4 bitop3:0x36
	v_bitop3_b32 v2, v130, v2, 6 bitop3:0x36
	v_lshl_or_b32 v6, v146, 7, s4
	v_lshlrev_b32_e32 v9, 4, v3
	v_lshlrev_b32_e32 v10, 4, v2
	s_and_b32 s4, s87, 3
	v_mov_b64_e32 v[2:3], s[2:3]
	s_lshl_b32 s14, s4, 8
	v_mad_i64_i32 v[4:5], s[4:5], v32, s13, v[2:3]
	v_lshl_add_u64 v[4:5], v[4:5], 0, v[20:21]
	v_lshl_add_u64 v[132:133], s[48:49], 0, v[4:5]
	v_and_b32_e32 v4, 7, v30
	v_mad_i64_i32 v[2:3], s[4:5], v31, s13, v[2:3]
	v_lshlrev_b32_e32 v4, 4, v4
	v_mov_b32_e32 v5, v1
	v_lshl_add_u64 v[2:3], v[2:3], 0, v[4:5]
	v_lshl_add_u64 v[134:135], s[48:49], 0, v[2:3]
	v_add_u32_e32 v145, v6, v7
	v_add_u32_e32 v147, v6, v8
	v_add_u32_e32 v148, v6, v9
	v_add_u32_e32 v149, v6, v10
	v_mov_b32_e32 v2, 0
	v_mov_b32_e32 v3, v150
	v_mov_b32_e32 v4, v150
	v_mov_b32_e32 v5, v150
	v_mov_b32_e32 v6, v150
	v_mov_b32_e32 v7, v150
	v_mov_b32_e32 v8, v150
	v_mov_b32_e32 v9, v150
	v_mov_b32_e32 v10, v150
	v_mov_b32_e32 v11, v150
	v_mov_b32_e32 v12, v150
	v_mov_b32_e32 v13, v150
	v_mov_b32_e32 v14, v150
	v_mov_b32_e32 v15, v150
	v_mov_b32_e32 v16, v150
	v_mov_b32_e32 v17, v150
	v_mov_b32_e32 v20, v150
	v_mov_b32_e32 v21, v150
	v_mov_b32_e32 v24, v150
	v_mov_b32_e32 v25, v150
	v_mov_b32_e32 v28, v150
	v_mov_b32_e32 v29, v150
	v_mov_b32_e32 v30, v150
	v_mov_b32_e32 v31, v150
	v_mov_b32_e32 v32, v150
	v_mov_b32_e32 v33, v150
	v_mov_b32_e32 v34, 0
	v_mov_b32_e32 v35, v150
	v_mov_b32_e32 v36, v150
	v_mov_b32_e32 v37, v150
	v_mov_b32_e32 v38, v150
	v_mov_b32_e32 v39, v150
	v_mov_b32_e32 v40, v150
	v_mov_b32_e32 v41, v150
	v_mov_b32_e32 v42, v150
	v_mov_b32_e32 v43, v150
	v_mov_b32_e32 v44, v150
	v_mov_b32_e32 v45, v150
	v_mov_b32_e32 v46, v150
	v_mov_b32_e32 v47, v150
	v_mov_b32_e32 v48, v150
	v_mov_b32_e32 v49, v150
	v_mov_b32_e32 v50, 0
	v_mov_b32_e32 v51, v150
	v_mov_b32_e32 v52, v150
	v_mov_b32_e32 v53, v150
	v_mov_b32_e32 v54, v150
	v_mov_b32_e32 v55, v150
	v_mov_b32_e32 v56, v150
	v_mov_b32_e32 v57, v150
	v_mov_b32_e32 v58, v150
	v_mov_b32_e32 v59, v150
	v_mov_b32_e32 v60, v150
	v_mov_b32_e32 v61, v150
	v_mov_b32_e32 v62, v150
	v_mov_b32_e32 v63, v150
	v_mov_b32_e32 v64, v150
	v_mov_b32_e32 v65, v150
	s_waitcnt lgkmcnt(0)
	s_barrier
; template <int DV, int NK, int MODE, bool FIXM, int GRP>
; DI void attn_job(char* lds_wg, const AttnJob& J) {
;     ...
;   bf16x8 qf[4];
;   const bf16_t* qrow = J.q + (size_t)r * UW + 8 * h;
; #pragma unroll
;   for (int ds = 0; ds < 4; ++ds) qf[ds] = *(const bf16x8*)(qrow + 16 * ds);
	v_readlane_b32 s45, v254, 34
	v_readlane_b32 s46, v254, 35
	v_readlane_b32 s47, v254, 36
	v_readlane_b32 s50, v254, 39
	v_readlane_b32 s51, v254, 40
	v_readlane_b32 s52, v254, 41
	v_readlane_b32 s53, v254, 42
	v_readlane_b32 s54, v254, 43
	v_readlane_b32 s55, v254, 44
	v_readlane_b32 s56, v254, 45
	v_readlane_b32 s57, v254, 46
	v_readlane_b32 s58, v254, 47
	v_readlane_b32 s59, v254, 48
	s_waitcnt vmcnt(4)
	v_lshlrev_b32_e32 v82, 16, v98
	v_and_b32_e32 v83, 0xffff0000, v98
	v_mul_f32_e32 v82, s7, v82
	v_mul_f32_e32 v83, s7, v83
	v_cvt_pk_bf16_f32 v98, v82, v83
	v_lshlrev_b32_e32 v82, 16, v99
	v_and_b32_e32 v83, 0xffff0000, v99
	v_mul_f32_e32 v82, s7, v82
	v_mul_f32_e32 v83, s7, v83
	v_cvt_pk_bf16_f32 v99, v82, v83
	v_lshlrev_b32_e32 v82, 16, v100
	v_and_b32_e32 v83, 0xffff0000, v100
	v_mul_f32_e32 v82, s7, v82
	v_mul_f32_e32 v83, s7, v83
	v_cvt_pk_bf16_f32 v100, v82, v83
	v_lshlrev_b32_e32 v82, 16, v101
	v_and_b32_e32 v83, 0xffff0000, v101
	v_mul_f32_e32 v82, s7, v82
	v_mul_f32_e32 v83, s7, v83
	v_cvt_pk_bf16_f32 v101, v82, v83
	v_lshlrev_b32_e32 v82, 16, v102
	v_and_b32_e32 v83, 0xffff0000, v102
	v_mul_f32_e32 v82, s7, v82
	v_mul_f32_e32 v83, s7, v83
	v_cvt_pk_bf16_f32 v102, v82, v83
	v_lshlrev_b32_e32 v82, 16, v103
	v_and_b32_e32 v83, 0xffff0000, v103
	v_mul_f32_e32 v82, s7, v82
	v_mul_f32_e32 v83, s7, v83
	v_cvt_pk_bf16_f32 v103, v82, v83
	v_lshlrev_b32_e32 v82, 16, v104
	v_and_b32_e32 v83, 0xffff0000, v104
	v_mul_f32_e32 v82, s7, v82
	v_mul_f32_e32 v83, s7, v83
	v_cvt_pk_bf16_f32 v104, v82, v83
	v_lshlrev_b32_e32 v82, 16, v105
	v_and_b32_e32 v83, 0xffff0000, v105
	v_mul_f32_e32 v82, s7, v82
	v_mul_f32_e32 v83, s7, v83
	v_cvt_pk_bf16_f32 v105, v82, v83
	v_lshlrev_b32_e32 v82, 16, v106
	v_and_b32_e32 v83, 0xffff0000, v106
	v_mul_f32_e32 v82, s7, v82
	v_mul_f32_e32 v83, s7, v83
	v_cvt_pk_bf16_f32 v106, v82, v83
	v_lshlrev_b32_e32 v82, 16, v107
	v_and_b32_e32 v83, 0xffff0000, v107
	v_mul_f32_e32 v82, s7, v82
	v_mul_f32_e32 v83, s7, v83
	v_cvt_pk_bf16_f32 v107, v82, v83
	v_lshlrev_b32_e32 v82, 16, v108
	v_and_b32_e32 v83, 0xffff0000, v108
	v_mul_f32_e32 v82, s7, v82
	v_mul_f32_e32 v83, s7, v83
	v_cvt_pk_bf16_f32 v108, v82, v83
	v_lshlrev_b32_e32 v82, 16, v109
	v_and_b32_e32 v83, 0xffff0000, v109
	v_mul_f32_e32 v82, s7, v82
	v_mul_f32_e32 v83, s7, v83
	v_cvt_pk_bf16_f32 v109, v82, v83
	v_lshlrev_b32_e32 v82, 16, v110
	v_and_b32_e32 v83, 0xffff0000, v110
	v_mul_f32_e32 v82, s7, v82
	v_mul_f32_e32 v83, s7, v83
	v_cvt_pk_bf16_f32 v110, v82, v83
	v_lshlrev_b32_e32 v82, 16, v111
	v_and_b32_e32 v83, 0xffff0000, v111
	v_mul_f32_e32 v82, s7, v82
	v_mul_f32_e32 v83, s7, v83
	v_cvt_pk_bf16_f32 v111, v82, v83
	v_lshlrev_b32_e32 v82, 16, v112
	v_and_b32_e32 v83, 0xffff0000, v112
	v_mul_f32_e32 v82, s7, v82
	v_mul_f32_e32 v83, s7, v83
	v_cvt_pk_bf16_f32 v112, v82, v83
	v_lshlrev_b32_e32 v82, 16, v113
	v_and_b32_e32 v83, 0xffff0000, v113
	v_mul_f32_e32 v82, s7, v82
	v_mul_f32_e32 v83, s7, v83
	v_cvt_pk_bf16_f32 v113, v82, v83

; template <int DV, int NK, int MODE, bool FIXM, int GRP>
; DI void attn_job(char* lds_wg, const AttnJob& J) {
;     ...
;       if (NDV == 2 || FIXM) {
;         bf16x8 ka[4], kb[4];
; #pragma unroll
;         for (int ds = 0; ds < 4; ++ds) { const int co = ((2 * ds + h) ^ ((r >> 1) & 7)) << 4; ka[ds] = *(const bf16x8*)(Kl + co); kb[ds] = *(const bf16x8*)(Kl + 4096 + co); }
; #pragma unroll
;         for (int ds = 0; ds < 4; ++ds) { sA = MFMA32(ka[ds], qf[ds], sA); sB = MFMA32(kb[ds], qf[ds], sB); }
;         __builtin_amdgcn_sched_group_barrier(0x100, 4, 0); __builtin_amdgcn_sched_group_barrier(0x008, 2, 0);
;         __builtin_amdgcn_sched_group_barrier(0x100, 2, 0); __builtin_amdgcn_sched_group_barrier(0x008, 2, 0);
;         __builtin_amdgcn_sched_group_barrier(0x100, 2, 0); __builtin_amdgcn_sched_group_barrier(0x008, 4, 0);
;       } else {
; #pragma unroll
;         for (int ds = 0; ds < 4; ++ds) {
;           const int co = ((2 * ds + h) ^ ((r >> 1) & 7)) << 4;
;           const bf16x8 ka = *(const bf16x8*)(Kl + co), kb = *(const bf16x8*)(Kl + 4096 + co);
;           sA = MFMA32(ka, qf[ds], sA); sB = MFMA32(kb, qf[ds], sB);
;         }
;       }
;       if (MODE == AM_SWA) {
;         const int qa = J.qpos0 + r, kbase = tile * 64 + 8 * h;
; #pragma unroll
;         for (int i = 0; i < 16; ++i) {
;           const int ka_ = kbase + 16 * (i >> 3) + (i & 7);
;           int d0 = qa - ka_; d0 = d0 < 0 ? -d0 : d0; if (d0 > 128) sA[i] = -INFINITY;
;           int d1 = qa - (ka_ + 32); d1 = d1 < 0 ? -d1 : d1; if (d1 > 128) sB[i] = -INFINITY;
;         }
;       }
;       if (FIXM) {
;         const float nm = -J.m_init;
; #pragma unroll
;         for (int i = 0; i < 16; ++i) { sA[i] = __builtin_amdgcn_exp2f(fmaf(sA[i], C, nm)); sB[i] = __builtin_amdgcn_exp2f(fmaf(sB[i], C, nm)); l += sA[i] + sB[i]; }
;     ...
;       if (FIXM) {
;         bf16x8 vf[4][NDV];
; #pragma unroll
;         for (int ks = 0; ks < 4; ++ks) {
; #pragma unroll
;           for (int d = 0; d < NDV; ++d) {
;             const s16x4 lo = __builtin_amdgcn_ds_read_tr16_b64_v4i16((LAS s16x4*)(Vl + ks * 2 * NDV * 512 + d * 512));
;             const s16x4 hi = __builtin_amdgcn_ds_read_tr16_b64_v4i16((LAS s16x4*)(Vl + ks * 2 * NDV * 512 + d * 512 + 256));
;             vf[ks][d] = __builtin_shufflevector(lo, hi, 0, 1, 2, 3, 4, 5, 6, 7);
;           }
;         }
; #pragma unroll
.LBB0_325:
	ds_read_b128 v[66:69], v145
	ds_read_b128 v[70:73], v145 offset:4096
	ds_read_b128 v[154:157], v147
	ds_read_b128 v[158:161], v147 offset:4096
	s_andn2_b64 vcc, exec, s[74:75]
	s_waitcnt lgkmcnt(3)
	v_mfma_f32_32x32x16_bf16 v[82:97], v[66:69], v[98:101], 0
	s_waitcnt lgkmcnt(2)
	v_mfma_f32_32x32x16_bf16 v[66:81], v[70:73], v[98:101], 0
	ds_read_b128 v[162:165], v148
	ds_read_b128 v[174:177], v148 offset:4096
	s_waitcnt lgkmcnt(3)
	v_mfma_f32_32x32x16_bf16 v[82:97], v[154:157], v[102:105], v[82:97]
	s_waitcnt lgkmcnt(2)
	v_mfma_f32_32x32x16_bf16 v[66:81], v[158:161], v[102:105], v[66:81]
	ds_read_b128 v[154:157], v149
	ds_read_b128 v[158:161], v149 offset:4096
	s_waitcnt lgkmcnt(3)
	v_mfma_f32_32x32x16_bf16 v[82:97], v[162:165], v[106:109], v[82:97]
	s_waitcnt lgkmcnt(1)
	v_mfma_f32_32x32x16_bf16 v[82:97], v[154:157], v[110:113], v[82:97]
	v_mfma_f32_32x32x16_bf16 v[66:81], v[174:177], v[106:109], v[66:81]
	s_nop 10
	v_exp_f32_e32 v153, v82
	v_exp_f32_e32 v154, v83
	v_exp_f32_e32 v155, v84
	v_exp_f32_e32 v156, v85
	s_waitcnt lgkmcnt(0)
	v_mfma_f32_32x32x16_bf16 v[66:81], v[158:161], v[110:113], v[66:81]
	v_exp_f32_e32 v158, v86
	v_exp_f32_e32 v157, v87
	v_exp_f32_e32 v159, v88
	v_exp_f32_e32 v160, v89
	ds_read_b64_tr_b16 v[86:87], v144 offset:16384
	ds_read_b64_tr_b16 v[88:89], v144 offset:16640
	ds_read_b64_tr_b16 v[174:175], v144 offset:16896
	ds_read_b64_tr_b16 v[176:177], v144 offset:17152
	ds_read_b64_tr_b16 v[178:179], v144 offset:17408
	ds_read_b64_tr_b16 v[180:181], v144 offset:17664
	ds_read_b64_tr_b16 v[182:183], v144 offset:17920
	ds_read_b64_tr_b16 v[184:185], v144 offset:18176
	v_cvt_pk_bf16_f32 v82, v153, v154
	v_cvt_pk_bf16_f32 v83, v155, v156
	v_cvt_pk_bf16_f32 v84, v158, v157
	v_cvt_pk_bf16_f32 v85, v159, v160
	ds_read_b64_tr_b16 v[186:187], v144 offset:20480
	ds_read_b64_tr_b16 v[188:189], v144 offset:20736
	ds_read_b64_tr_b16 v[190:191], v144 offset:20992
	ds_read_b64_tr_b16 v[192:193], v144 offset:21248
	ds_read_b64_tr_b16 v[194:195], v144 offset:21504
	ds_read_b64_tr_b16 v[196:197], v144 offset:21760
	ds_read_b64_tr_b16 v[198:199], v144 offset:22016
	ds_read_b64_tr_b16 v[200:201], v144 offset:22272
	s_waitcnt lgkmcnt(14)
	v_mfma_f32_32x32x16_bf16 v[50:65], v[86:89], v[82:85], v[50:65]
	v_exp_f32_e32 v168, v90
	v_exp_f32_e32 v162, v91
	v_exp_f32_e32 v163, v92
	v_exp_f32_e32 v169, v93
	s_waitcnt lgkmcnt(12)
	v_mfma_f32_32x32x16_bf16 v[34:49], v[174:177], v[82:85], v[34:49]
	v_exp_f32_e32 v164, v94
	v_exp_f32_e32 v165, v95
	v_exp_f32_e32 v170, v96
	v_exp_f32_e32 v161, v97
	s_waitcnt lgkmcnt(10)
	v_mfma_f32_32x32x16_bf16 v[18:33], v[178:181], v[82:85], v[18:33]
	v_exp_f32_e32 v176, v66
	v_exp_f32_e32 v177, v67
	v_exp_f32_e32 v178, v68
	s_waitcnt lgkmcnt(8)
	v_mfma_f32_32x32x16_bf16 v[2:17], v[182:185], v[82:85], v[2:17]
	v_cvt_pk_bf16_f32 v86, v168, v162
	v_cvt_pk_bf16_f32 v87, v163, v169
	v_cvt_pk_bf16_f32 v88, v164, v165
	v_cvt_pk_bf16_f32 v89, v170, v161
	ds_read_b64_tr_b16 v[82:83], v144 offset:24576
	ds_read_b64_tr_b16 v[84:85], v144 offset:24832
	ds_read_b64_tr_b16 v[90:91], v144 offset:25088
	ds_read_b64_tr_b16 v[92:93], v144 offset:25344
	ds_read_b64_tr_b16 v[94:95], v144 offset:25600
	ds_read_b64_tr_b16 v[96:97], v144 offset:25856
	ds_read_b64_tr_b16 v[202:203], v144 offset:26112
	ds_read_b64_tr_b16 v[204:205], v144 offset:26368
	v_exp_f32_e32 v179, v69
	s_waitcnt lgkmcnt(14)
	v_mfma_f32_32x32x16_bf16 v[50:65], v[186:189], v[86:89], v[50:65]
	v_exp_f32_e32 v180, v70
	v_exp_f32_e32 v173, v71
	v_exp_f32_e32 v174, v72
	v_exp_f32_e32 v175, v73
	s_waitcnt lgkmcnt(12)
	v_mfma_f32_32x32x16_bf16 v[34:49], v[190:193], v[86:89], v[34:49]
	v_exp_f32_e32 v186, v74
	v_exp_f32_e32 v182, v75
	v_cvt_pk_bf16_f32 v66, v176, v177
	v_cvt_pk_bf16_f32 v67, v178, v179
	s_waitcnt lgkmcnt(10)
	v_mfma_f32_32x32x16_bf16 v[18:33], v[194:197], v[86:89], v[18:33]
	v_cvt_pk_bf16_f32 v68, v180, v173
	v_cvt_pk_bf16_f32 v69, v174, v175
	v_exp_f32_e32 v183, v76
	v_exp_f32_e32 v187, v77
	v_exp_f32_e32 v184, v78
	s_waitcnt lgkmcnt(8)
	v_mfma_f32_32x32x16_bf16 v[2:17], v[198:201], v[86:89], v[2:17]
	ds_read_b64_tr_b16 v[70:71], v144 offset:28672
	ds_read_b64_tr_b16 v[72:73], v144 offset:28928
	ds_read_b64_tr_b16 v[86:87], v144 offset:29184
	ds_read_b64_tr_b16 v[88:89], v144 offset:29440
	ds_read_b64_tr_b16 v[190:191], v144 offset:29696
	ds_read_b64_tr_b16 v[192:193], v144 offset:29952
	ds_read_b64_tr_b16 v[194:195], v144 offset:30208
	ds_read_b64_tr_b16 v[196:197], v144 offset:30464
	s_waitcnt lgkmcnt(14)
	v_mfma_f32_32x32x16_bf16 v[50:65], v[82:85], v[66:69], v[50:65]
	v_exp_f32_e32 v185, v79
	v_exp_f32_e32 v188, v80
	s_waitcnt lgkmcnt(0)
	s_barrier
	v_mfma_f32_32x32x16_bf16 v[34:49], v[90:93], v[66:69], v[34:49]
	v_mfma_f32_32x32x16_bf16 v[18:33], v[94:97], v[66:69], v[18:33]
	v_mfma_f32_32x32x16_bf16 v[2:17], v[202:205], v[66:69], v[2:17]
	v_exp_f32_e32 v181, v81
	v_cvt_pk_bf16_f32 v66, v186, v182
	v_cvt_pk_bf16_f32 v67, v183, v187
	v_cvt_pk_bf16_f32 v68, v184, v185
	v_cvt_pk_bf16_f32 v69, v188, v181
	s_nop 1
	v_mfma_f32_32x32x16_bf16 v[50:65], v[70:73], v[66:69], v[50:65]
	v_mfma_f32_32x32x16_bf16 v[34:49], v[86:89], v[66:69], v[34:49]
	v_mfma_f32_32x32x16_bf16 v[18:33], v[190:193], v[66:69], v[18:33]
	v_mfma_f32_32x32x16_bf16 v[2:17], v[194:197], v[66:69], v[2:17]
	s_cbranch_vccnz .LBB0_327
	s_waitcnt vmcnt(3)
	ds_write_b128 v141, v[114:117]
	s_waitcnt vmcnt(2)
	ds_write_b128 v141, v[118:121] offset:8192
	s_waitcnt vmcnt(1)
	ds_write_b128 v151, v[122:125] offset:16384
	s_waitcnt vmcnt(0)
	ds_write_b128 v152, v[126:129] offset:16384

; template <int DV, int NK, int MODE, bool FIXM, int GRP>
; DI void attn_job(char* lds_wg, const AttnJob& J) {
;     ...
;       if (NDV == 2 || FIXM) {
;         bf16x8 ka[4], kb[4];
; #pragma unroll
;         for (int ds = 0; ds < 4; ++ds) { const int co = ((2 * ds + h) ^ ((r >> 1) & 7)) << 4; ka[ds] = *(const bf16x8*)(Kl + co); kb[ds] = *(const bf16x8*)(Kl + 4096 + co); }
; #pragma unroll
;         for (int ds = 0; ds < 4; ++ds) { sA = MFMA32(ka[ds], qf[ds], sA); sB = MFMA32(kb[ds], qf[ds], sB); }
;         __builtin_amdgcn_sched_group_barrier(0x100, 4, 0); __builtin_amdgcn_sched_group_barrier(0x008, 2, 0);
;         __builtin_amdgcn_sched_group_barrier(0x100, 2, 0); __builtin_amdgcn_sched_group_barrier(0x008, 2, 0);
;         __builtin_amdgcn_sched_group_barrier(0x100, 2, 0); __builtin_amdgcn_sched_group_barrier(0x008, 4, 0);
;       } else {
; #pragma unroll
;         for (int ds = 0; ds < 4; ++ds) {
;           const int co = ((2 * ds + h) ^ ((r >> 1) & 7)) << 4;
;           const bf16x8 ka = *(const bf16x8*)(Kl + co), kb = *(const bf16x8*)(Kl + 4096 + co);
;           sA = MFMA32(ka, qf[ds], sA); sB = MFMA32(kb, qf[ds], sB);
;         }
;       }
;       if (MODE == AM_SWA) {
;         const int qa = J.qpos0 + r, kbase = tile * 64 + 8 * h;
; #pragma unroll
;         for (int i = 0; i < 16; ++i) {
;           const int ka_ = kbase + 16 * (i >> 3) + (i & 7);
;           int d0 = qa - ka_; d0 = d0 < 0 ? -d0 : d0; if (d0 > 128) sA[i] = -INFINITY;
;           int d1 = qa - (ka_ + 32); d1 = d1 < 0 ? -d1 : d1; if (d1 > 128) sB[i] = -INFINITY;
;         }
;       }
;       if (FIXM) {
;         const float nm = -J.m_init;
; #pragma unroll
;         for (int i = 0; i < 16; ++i) { sA[i] = __builtin_amdgcn_exp2f(fmaf(sA[i], C, nm)); sB[i] = __builtin_amdgcn_exp2f(fmaf(sB[i], C, nm)); l += sA[i] + sB[i]; }
;     ...
;       bf16x8 pf[4];
;       { u32x4 w;
;         w.x = cvtpk(sA[0], sA[1]); w.y = cvtpk(sA[2], sA[3]); w.z = cvtpk(sA[4], sA[5]); w.w = cvtpk(sA[6], sA[7]); pf[0] = __builtin_bit_cast(bf16x8, w);
;         w.x = cvtpk(sA[8], sA[9]); w.y = cvtpk(sA[10], sA[11]); w.z = cvtpk(sA[12], sA[13]); w.w = cvtpk(sA[14], sA[15]); pf[1] = __builtin_bit_cast(bf16x8, w);
;         w.x = cvtpk(sB[0], sB[1]); w.y = cvtpk(sB[2], sB[3]); w.z = cvtpk(sB[4], sB[5]); w.w = cvtpk(sB[6], sB[7]); pf[2] = __builtin_bit_cast(bf16x8, w);
.LBB0_329:
	ds_read_b128 v[66:69], v145 offset:32768
	ds_read_b128 v[70:73], v145 offset:36864
	ds_read_b128 v[136:139], v147 offset:32768
	ds_read_b128 v[190:193], v147 offset:36864
	v_lshl_add_u64 v[132:133], v[132:133], 0, s[94:95]
	v_lshl_add_u64 v[134:135], v[134:135], 0, s[94:95]
	s_and_b64 vcc, exec, s[4:5]
	s_waitcnt lgkmcnt(3)
	v_mfma_f32_32x32x16_bf16 v[82:97], v[66:69], v[98:101], 0
	s_waitcnt lgkmcnt(2)
	v_mfma_f32_32x32x16_bf16 v[66:81], v[70:73], v[98:101], 0
	ds_read_b128 v[194:197], v148 offset:32768
	ds_read_b128 v[198:201], v148 offset:36864
	s_waitcnt lgkmcnt(3)
	v_mfma_f32_32x32x16_bf16 v[82:97], v[136:139], v[102:105], v[82:97]
	v_add_f32_e32 v136, v153, v176
	v_add_f32_e32 v136, v150, v136
	v_add_f32_e32 v137, v154, v177
	v_add_f32_e32 v136, v137, v136
	v_add_f32_e32 v137, v155, v178
	v_add_f32_e32 v136, v137, v136
	v_add_f32_e32 v137, v156, v179
	s_waitcnt lgkmcnt(2)
	v_mfma_f32_32x32x16_bf16 v[66:81], v[190:193], v[102:105], v[66:81]
	v_add_f32_e32 v136, v137, v136
	v_add_f32_e32 v137, v158, v180
	v_add_f32_e32 v154, v137, v136
	ds_read_b128 v[136:139], v149 offset:32768
	ds_read_b128 v[150:153], v149 offset:36864
	v_add_f32_e32 v155, v157, v173
	v_add_f32_e32 v154, v155, v154
	s_waitcnt lgkmcnt(3)
	v_mfma_f32_32x32x16_bf16 v[82:97], v[194:197], v[106:109], v[82:97]
	v_add_f32_e32 v155, v159, v174
	v_add_f32_e32 v154, v155, v154
	v_add_f32_e32 v155, v160, v175
	v_add_f32_e32 v154, v155, v154
	v_add_f32_e32 v155, v168, v186
	v_add_f32_e32 v154, v155, v154
	v_add_f32_e32 v155, v162, v182
	s_waitcnt lgkmcnt(2)
	v_mfma_f32_32x32x16_bf16 v[66:81], v[198:201], v[106:109], v[66:81]
	v_add_f32_e32 v154, v155, v154
	v_add_f32_e32 v155, v163, v183
	v_add_f32_e32 v154, v155, v154
	v_add_f32_e32 v155, v169, v187
	v_add_f32_e32 v154, v155, v154
	s_waitcnt lgkmcnt(1)
	v_mfma_f32_32x32x16_bf16 v[82:97], v[136:139], v[110:113], v[82:97]
	v_add_f32_e32 v136, v164, v184
	v_add_f32_e32 v136, v136, v154
	v_add_f32_e32 v137, v165, v185
	v_add_f32_e32 v136, v137, v136
	v_add_f32_e32 v137, v170, v188
	s_nop 6
	s_waitcnt lgkmcnt(0)
	v_mfma_f32_32x32x16_bf16 v[66:81], v[150:153], v[110:113], v[66:81]
	v_exp_f32_e32 v82, v82
	v_exp_f32_e32 v83, v83
	ds_read_b64_tr_b16 v[138:139], v144 offset:50432
	ds_read_b64_tr_b16 v[150:151], v144 offset:50688
	ds_read_b64_tr_b16 v[152:153], v144 offset:50944
	ds_read_b64_tr_b16 v[154:155], v144 offset:53248
	s_nop 4
	v_exp_f32_e32 v170, v66
	v_exp_f32_e32 v173, v67
	v_add_f32_e32 v66, v137, v136
	v_add_f32_e32 v136, v161, v181
	v_exp_f32_e32 v67, v84
	v_exp_f32_e32 v181, v68
	v_add_f32_e32 v66, v136, v66
	v_add_f32_e32 v136, v82, v170
	v_add_f32_e32 v66, v66, v136
	v_add_f32_e32 v68, v83, v173
	v_add_f32_e32 v66, v68, v66
	v_add_f32_e32 v68, v67, v181
	v_add_f32_e32 v169, v68, v66
	v_exp_f32_e32 v179, v85
	v_exp_f32_e32 v183, v69
	v_exp_f32_e32 v185, v86
	v_exp_f32_e32 v187, v70
	v_exp_f32_e32 v70, v87
	v_exp_f32_e32 v188, v88
	v_exp_f32_e32 v168, v89
	v_cvt_pk_bf16_f32 v66, v82, v83
	ds_read_b64_tr_b16 v[82:83], v144 offset:49152
	ds_read_b64_tr_b16 v[84:85], v144 offset:49408
	v_exp_f32_e32 v178, v71
	ds_read_b64_tr_b16 v[86:87], v144 offset:49664
	ds_read_b64_tr_b16 v[88:89], v144 offset:49920
	v_exp_f32_e32 v189, v90
	ds_read_b64_tr_b16 v[136:137], v144 offset:50176
	v_exp_f32_e32 v180, v91
	v_exp_f32_e32 v190, v92
	v_exp_f32_e32 v182, v93
	v_exp_f32_e32 v191, v94
	v_exp_f32_e32 v184, v95
	v_cvt_pk_bf16_f32 v67, v67, v179
	v_cvt_pk_bf16_f32 v68, v185, v70
	v_cvt_pk_bf16_f32 v69, v188, v168
	ds_read_b64_tr_b16 v[156:157], v144 offset:53504
	v_exp_f32_e32 v192, v96
	ds_read_b64_tr_b16 v[158:159], v144 offset:53760
	ds_read_b64_tr_b16 v[160:161], v144 offset:54016
	ds_read_b64_tr_b16 v[162:163], v144 offset:54272
	ds_read_b64_tr_b16 v[164:165], v144 offset:54528
	ds_read_b64_tr_b16 v[174:175], v144 offset:54784
	ds_read_b64_tr_b16 v[176:177], v144 offset:55040
	s_waitcnt lgkmcnt(10)
	v_mfma_f32_32x32x16_bf16 v[50:65], v[82:85], v[66:69], v[50:65]
	v_exp_f32_e32 v186, v97
	v_add_f32_e32 v71, v179, v183
	v_add_f32_e32 v179, v71, v169
	v_add_f32_e32 v71, v185, v187
	v_pk_add_f32 v[70:71], v[70:71], v[178:179]
	v_cvt_pk_bf16_f32 v82, v189, v180
	v_cvt_pk_bf16_f32 v83, v190, v182
	s_waitcnt lgkmcnt(8)
	v_mfma_f32_32x32x16_bf16 v[34:49], v[86:89], v[66:69], v[34:49]
	v_cvt_pk_bf16_f32 v84, v191, v184
	v_cvt_pk_bf16_f32 v85, v192, v186
	s_waitcnt lgkmcnt(7)
	v_mfma_f32_32x32x16_bf16 v[18:33], v[136:139], v[66:69], v[18:33]
	v_add_f32_e64 v136, v70, v70
	v_add_f32_e64 v137, v70, v71
	v_exp_f32_e32 v138, v72
	v_exp_f32_e32 v136, v73
	v_cvt_pk_bf16_f32 v72, v187, v178
	v_add_f32_e32 v169, v188, v138
	v_mfma_f32_32x32x16_bf16 v[2:17], v[150:153], v[66:69], v[2:17]
	ds_read_b64_tr_b16 v[66:67], v144 offset:57344
	ds_read_b64_tr_b16 v[68:69], v144 offset:57600
	ds_read_b64_tr_b16 v[86:87], v144 offset:57856
	ds_read_b64_tr_b16 v[88:89], v144 offset:58112
	ds_read_b64_tr_b16 v[90:91], v144 offset:58368
	ds_read_b64_tr_b16 v[92:93], v144 offset:58624
	ds_read_b64_tr_b16 v[94:95], v144 offset:58880
	ds_read_b64_tr_b16 v[96:97], v144 offset:59136
	s_waitcnt lgkmcnt(14)
	v_mfma_f32_32x32x16_bf16 v[50:65], v[154:157], v[82:85], v[50:65]
	v_add_f32_e64 v70, v168, v136
	v_add_f32_e64 v71, v169, v137
	v_cvt_pk_bf16_f32 v73, v138, v136
	s_waitcnt lgkmcnt(12)
	v_mfma_f32_32x32x16_bf16 v[34:49], v[158:161], v[82:85], v[34:49]
	v_add_f32_e64 v158, v70, v70
	v_add_f32_e64 v159, v70, v71
	v_exp_f32_e32 v160, v74
	v_exp_f32_e32 v158, v75
	v_cvt_pk_bf16_f32 v70, v170, v173
	v_cvt_pk_bf16_f32 v71, v181, v183
	v_add_f32_e32 v181, v189, v160
	s_waitcnt lgkmcnt(10)
	v_mfma_f32_32x32x16_bf16 v[18:33], v[162:165], v[82:85], v[18:33]
	s_waitcnt lgkmcnt(8)
	v_mfma_f32_32x32x16_bf16 v[2:17], v[174:177], v[82:85], v[2:17]
	ds_read_b64_tr_b16 v[82:83], v144 offset:61440
	ds_read_b64_tr_b16 v[84:85], v144 offset:61696
	ds_read_b64_tr_b16 v[136:137], v144 offset:61952
	ds_read_b64_tr_b16 v[138:139], v144 offset:62208
	ds_read_b64_tr_b16 v[150:151], v144 offset:62464
	ds_read_b64_tr_b16 v[152:153], v144 offset:62720
	ds_read_b64_tr_b16 v[154:155], v144 offset:62976
	ds_read_b64_tr_b16 v[156:157], v144 offset:63232
	s_waitcnt lgkmcnt(14)
	v_mfma_f32_32x32x16_bf16 v[50:65], v[66:69], v[70:73], v[50:65]
	v_add_f32_e64 v66, v180, v158
	v_add_f32_e64 v67, v181, v159
	s_waitcnt lgkmcnt(0)
	v_add_f32_e64 v68, v66, v66
	v_add_f32_e64 v69, v66, v67
	v_exp_f32_e32 v159, v76
	v_exp_f32_e32 v68, v77
	v_mfma_f32_32x32x16_bf16 v[34:49], v[86:89], v[70:73], v[34:49]
	v_add_f32_e32 v183, v190, v159
	s_barrier
; #define LAS __attribute__((address_space(3)))
; template <int DV, int NK, int MODE, bool FIXM, int GRP>
; DI void attn_job(char* lds_wg, const AttnJob& J) {
;     ...
;         for (int i = 0; i < 16; ++i) { sA[i] = __builtin_amdgcn_exp2f(fmaf(sA[i], C, nm)); sB[i] = __builtin_amdgcn_exp2f(fmaf(sB[i], C, nm)); l += sA[i] + sB[i]; }
;       } else {
;       float mx = sA[0];
; #pragma unroll
;       for (int i = 1; i < 16; ++i) mx = fmaxf(mx, sA[i]);
; #pragma unroll
;       for (int i = 0; i < 16; ++i) mx = fmaxf(mx, sB[i]);
;       mx = swapmax(mx);
;       const float mn = fmaxf(m, mx * C);
;       const float alpha = __builtin_amdgcn_exp2f(m - mn);
;       m = mn;
;       float ps = 0.f;
; #pragma unroll
;       for (int i = 0; i < 16; ++i) { sA[i] = __builtin_amdgcn_exp2f(fmaf(sA[i], C, -mn)); sB[i] = __builtin_amdgcn_exp2f(fmaf(sB[i], C, -mn)); ps += sA[i] + sB[i]; }
;       l = l * alpha + ps;
; #pragma unroll
;       for (int d = 0; d < NDV; ++d)
; #pragma unroll
;         for (int i = 0; i < 16; ++i) O[d][i] *= alpha;
;       }
;       bf16x8 pf[4];
;       { u32x4 w;
;         w.x = cvtpk(sA[0], sA[1]); w.y = cvtpk(sA[2], sA[3]); w.z = cvtpk(sA[4], sA[5]); w.w = cvtpk(sA[6], sA[7]); pf[0] = __builtin_bit_cast(bf16x8, w);
;         w.x = cvtpk(sA[8], sA[9]); w.y = cvtpk(sA[10], sA[11]); w.z = cvtpk(sA[12], sA[13]); w.w = cvtpk(sA[14], sA[15]); pf[1] = __builtin_bit_cast(bf16x8, w);
;         w.x = cvtpk(sB[0], sB[1]); w.y = cvtpk(sB[2], sB[3]); w.z = cvtpk(sB[4], sB[5]); w.w = cvtpk(sB[6], sB[7]); pf[2] = __builtin_bit_cast(bf16x8, w);
;         w.x = cvtpk(sB[8], sB[9]); w.y = cvtpk(sB[10], sB[11]); w.z = cvtpk(sB[12], sB[13]); w.w = cvtpk(sB[14], sB[15]); pf[3] = __builtin_bit_cast(bf16x8, w); }
;       const char* Vl = lds + stage * 32768 + NK * 8192 + vrd;
;       if (FIXM) {
;         bf16x8 vf[4][NDV];
; #pragma unroll
;         for (int ks = 0; ks < 4; ++ks) {
; #pragma unroll
;           for (int d = 0; d < NDV; ++d) {
;             const s16x4 lo = __builtin_amdgcn_ds_read_tr16_b64_v4i16((LAS s16x4*)(Vl + ks * 2 * NDV * 512 + d * 512));
;             const s16x4 hi = __builtin_amdgcn_ds_read_tr16_b64_v4i16((LAS s16x4*)(Vl + ks * 2 * NDV * 512 + d * 512 + 256));
;             vf[ks][d] = __builtin_shufflevector(lo, hi, 0, 1, 2, 3, 4, 5, 6, 7);
;           }
;         }
; #pragma unroll
;         for (int ks = 0; ks < 4; ++ks) {
; #pragma unroll
	v_add_f32_e64 v66, v182, v68
	v_add_f32_e64 v67, v183, v69
	v_add_f32_e64 v74, v66, v66
	v_add_f32_e64 v75, v66, v67
	v_exp_f32_e32 v69, v78
	v_exp_f32_e32 v74, v79
	v_mfma_f32_32x32x16_bf16 v[18:33], v[90:93], v[70:73], v[18:33]
	v_add_f32_e32 v185, v191, v69
	v_add_f32_e64 v66, v184, v74
	v_add_f32_e64 v67, v185, v75
	v_add_f32_e64 v76, v66, v66
	v_add_f32_e64 v77, v66, v67
	v_cvt_pk_bf16_f32 v67, v159, v68
	v_cvt_pk_bf16_f32 v68, v69, v74
	v_mfma_f32_32x32x16_bf16 v[2:17], v[94:97], v[70:73], v[2:17]
	v_exp_f32_e32 v70, v80
	v_exp_f32_e32 v76, v81
	v_cvt_pk_bf16_f32 v66, v160, v158
	v_add_f32_e32 v187, v192, v70
	v_cvt_pk_bf16_f32 v69, v70, v76
	v_pk_add_f32 v[70:71], v[186:187], v[76:77]
	s_nop 0
	v_mfma_f32_32x32x16_bf16 v[50:65], v[82:85], v[66:69], v[50:65]
	v_mfma_f32_32x32x16_bf16 v[34:49], v[136:139], v[66:69], v[34:49]
	v_mfma_f32_32x32x16_bf16 v[18:33], v[150:153], v[66:69], v[18:33]
	v_add_f32_e32 v150, v70, v71
	v_mfma_f32_32x32x16_bf16 v[2:17], v[154:157], v[66:69], v[2:17]
	s_cbranch_vccnz .LBB0_331
	s_mov_b32 s41, s40
	s_branch .LBB0_323

; DI int ltid() { int t; asm volatile("v_mov_b32 %0, %1" : "=v"(t) : "v"(threadIdx.x)); return t; }
; #define A_LOAD(t, rk, rv) do { const size_t kb_ = (size_t)(t) * 64; \
;     _Pragma("unroll") for (int s = 0; s < NK; ++s) _Pragma("unroll") for (int i = 0; i < KI; ++i) rk[s][i] = *(const u32x4*)(J.k[s] + (kb_ + ksrow + 32 * i) * J.ldk + ksch * 8); \
;     _Pragma("unroll") for (int i = 0; i < VI; ++i) rv[i] = *(const u32x4*)(J.v + (kb_ + vkey0 + (STN / VCH) * i) * J.ldv + vc8); } while (0)
; template <int DV, int NK, int MODE, bool FIXM, int GRP>
; DI void attn_job(char* lds_wg, const AttnJob& J) {
;     ...
;   const int tid_wg = ltid(), tid = tid_wg & (AT - 1), lane = tid & 63, wid = __builtin_amdgcn_readfirstlane(tid >> 6), r = lane & 31, h = lane >> 5;
;   constexpr bool SHR = FIXM || MODE == AM_SWA;
;   constexpr int STN = SHR ? NTHREADS : AT;
;   char* lds = lds_wg + (SHR ? 0 : GRP * 65536);
;   const int st_ = SHR ? tid_wg : tid;
;   const int kstream = (NK == 2) ? (wid & 1) : 0;
;   bf16x8 qf[4];
;   const bf16_t* qrow = J.q + (size_t)r * UW + 8 * h;
; #pragma unroll
;   for (int ds = 0; ds < 4; ++ds) qf[ds] = *(const bf16x8*)(qrow + 16 * ds);
;   f32x16 O[NDV];
; #pragma unroll
;   for (int d = 0; d < NDV; ++d)
; #pragma unroll
;     for (int i = 0; i < 16; ++i) O[d][i] = 0.f;
;   float m = J.m_init, l = (h == 0) ? J.l_init : 0.f;
;   f32x16 Osum;
; #pragma unroll
;   for (int i = 0; i < 16; ++i) Osum[i] = 0.f;
;   const bf16x8 ones = {0x3F80, 0x3F80, 0x3F80, 0x3F80, 0x3F80, 0x3F80, 0x3F80, 0x3F80};
;   constexpr int KI = 512 / STN;
;   const int ksrow = st_ >> 3, ksch = st_ & 7;
;   const int kpi = (ksrow & ~12) | ((ksrow & 4) << 1) | ((ksrow & 8) >> 1);
;   const int ksoff = kpi * 128 + ((ksch ^ ((kpi >> 1) & 7)) << 4);
;   constexpr int VCH = DV / 8;
;   constexpr int VI = (64 * VCH) / STN;
;   const int vkey0 = st_ / VCH, vc8 = (st_ % VCH) * 8;
;   u32x4 rk0[NK][KI], rv0[VI], rk1[NK][KI], rv1[VI];
;     ...
;   const int nt = J.tile_hi - J.tile_lo;
;   constexpr bool DEEP2 = FIXM || MODE != AM_DIFF;
;   constexpr bool ONESET = FIXM;
;   A_LOAD(J.tile_lo, rk0, rv0); A_WRITE(0, rk0, rv0); if (ONESET) A_LOAD(J.tile_lo + 1, rk0, rv0); else if (DEEP2) A_LOAD(J.tile_lo + 1, rk1, rv1); __syncthreads();
.LBB0_338:
	s_and_b64 vcc, exec, s[4:5]
	s_cbranch_vccz .LBB0_292
	v_mov_b32 v30, v212
	s_nop 5
	v_mov_b64_e32 v[2:3], s[68:69]
	v_ashrrev_i32_e32 v0, 31, v30
	v_lshrrev_b32_e32 v0, 28, v0
	v_add_u32_e32 v0, v30, v0
	v_ashrrev_i32_e32 v32, 4, v0
	v_and_b32_e32 v0, -16, v0
	v_sub_u32_e32 v33, v30, v0
	v_lshlrev_b32_e32 v10, 3, v33
	v_ashrrev_i32_e32 v11, 31, v10
	v_lshlrev_b64 v[20:21], 1, v[10:11]
	v_lshl_add_u64 v[10:11], s[68:69], 0, v[20:21]
	v_ashrrev_i32_e32 v31, 3, v30
	v_lshlrev_b32_e32 v34, 4, v30
	v_mad_i64_i32 v[22:23], s[4:5], v32, s13, v[10:11]
	v_mad_i64_i32 v[2:3], s[4:5], v31, s13, v[2:3]
	v_and_b32_e32 v18, 0x70, v34
	v_mov_b32_e32 v19, v1
	v_add_co_u32_e32 v14, vcc, s22, v22
	v_lshl_add_u64 v[6:7], v[2:3], 0, v[18:19]
	s_nop 0
	v_addc_co_u32_e32 v15, vcc, 0, v23, vcc
	global_load_dwordx4 v[2:5], v[6:7], off offset:2560
	s_nop 0
	global_load_dwordx4 v[6:9], v[6:7], off offset:2688
	s_nop 0
	global_load_dwordx4 v[10:13], v[22:23], off offset:3584
	s_nop 0
	global_load_dwordx4 v[14:17], v[14:15], off offset:3584
	v_mov_b64_e32 v[24:25], s[96:97]
	v_and_b32_e32 v146, 31, v30
	v_bfe_u32 v130, v30, 5, 1
	v_lshlrev_b32_e32 v28, 1, v31
	v_lshrrev_b32_e32 v29, 1, v31
	v_mad_u64_u32 v[24:25], s[4:5], v146, s13, v[24:25]
	v_lshlrev_b32_e32 v0, 4, v130
	v_and_b32_e32 v36, -13, v31
	v_mad_i64_i32 v[26:27], s[4:5], v31, s13, v[166:167]
	v_and_b32_e32 v37, 8, v28
	v_and_b32_e32 v38, 4, v29
	v_lshl_add_u64 v[24:25], v[24:25], 0, v[0:1]
	v_lshl_add_u64 v[28:29], s[70:71], 0, v[26:27]
	v_lshl_add_u64 v[26:27], s[72:73], 0, v[26:27]
	v_or3_b32 v36, v37, v36, v38
	global_load_dwordx4 v[98:101], v[24:25], off offset:1536
	global_load_dwordx4 v[102:105], v[24:25], off offset:1568
	global_load_dwordx4 v[106:109], v[24:25], off offset:1600
	global_load_dwordx4 v[110:113], v[24:25], off offset:1632
	v_lshl_add_u64 v[24:25], v[28:29], 0, v[18:19]
	v_lshl_add_u64 v[18:19], v[26:27], 0, v[18:19]
	v_lshrrev_b32_e32 v27, 1, v36
	v_lshlrev_b32_e32 v26, 7, v36
	v_lshrrev_b32_e32 v29, 1, v32
	v_add_u32_e32 v36, 32, v32
	global_load_dwordx4 v[114:117], v[24:25], off
	global_load_dwordx4 v[118:121], v[18:19], off
	v_xor_b32_e32 v18, v27, v30
	v_ashrrev_i32_e32 v19, 2, v33
	v_and_b32_e32 v25, 0x7ffffc, v29
	v_lshrrev_b32_e32 v27, 1, v36
	v_lshlrev_b32_e32 v18, 4, v18
	v_add_lshl_u32 v140, v25, v19, 9
	v_and_b32_e32 v25, 0x7ffffc, v27
	v_and_or_b32 v141, v18, s12, v26
	v_add_co_u32_e32 v18, vcc, s34, v22
	v_add_lshl_u32 v143, v25, v19, 9
	s_nop 0
	v_addc_co_u32_e32 v19, vcc, 0, v23, vcc
	v_add_co_u32_e32 v22, vcc, s20, v22
	v_lshlrev_b32_e32 v24, 4, v33
	s_nop 0
	v_addc_co_u32_e32 v23, vcc, 0, v23, vcc
	global_load_dwordx4 v[122:125], v[18:19], off offset:3584
	global_load_dwordx4 v[126:129], v[22:23], off offset:3584
	v_lshlrev_b32_e32 v28, 6, v32
	v_and_b32_e32 v24, 48, v24
	v_and_or_b32 v142, v28, s6, v24
	v_or_b32_e32 v24, v142, v140
	v_or_b32_e32 v25, v142, v143
	v_lshrrev_b32_e32 v35, 5, v30
	v_readlane_b32 s44, v254, 33
	v_readfirstlane_b32 s38, v30
	v_readlane_b32 s48, v254, 37
	v_readlane_b32 s49, v254, 38
	s_lshl_b32 s4, s38, 7
	s_and_b32 s4, s4, 0x2000
	v_mov_b32_e32 v150, 0
	s_mov_b32 s41, 0
	s_lshr_b32 s39, s38, 6
	v_mov_b32_e32 v18, 0
	v_mov_b32_e32 v19, v150
	v_mov_b32_e32 v22, v150
	v_mov_b32_e32 v23, v150
	v_mov_b32_e32 v26, v150
	v_mov_b32_e32 v27, v150
	s_waitcnt vmcnt(11)
	ds_write_b128 v141, v[2:5]
	s_waitcnt vmcnt(10)
	ds_write_b128 v141, v[6:9] offset:8192
	s_waitcnt vmcnt(9)
	ds_write_b128 v24, v[10:13] offset:16384
	s_waitcnt vmcnt(8)
	ds_write_b128 v25, v[14:17] offset:16384
	v_lshlrev_b32_e32 v4, 2, v30
	v_and_b32_e32 v5, 16, v30
	v_and_or_b32 v4, v4, 12, v5
	v_lshlrev_b32_e32 v2, 11, v130
	v_and_b32_e32 v3, 0xc0, v34
	v_lshlrev_b32_e32 v4, 1, v4
	v_or3_b32 v144, v2, v3, v4
	v_bfe_u32 v2, v30, 1, 3
	v_bitop3_b32 v3, v35, v2, 1 bitop3:0x6c
	v_lshlrev_b32_e32 v7, 4, v3
	v_bitop3_b32 v3, v130, v2, 2 bitop3:0x36
	v_lshlrev_b32_e32 v8, 4, v3
	v_bitop3_b32 v3, v130, v2, 4 bitop3:0x36
	v_bitop3_b32 v2, v130, v2, 6 bitop3:0x36
	v_lshlrev_b32_e32 v9, 4, v3
	v_lshlrev_b32_e32 v10, 4, v2
	v_mov_b64_e32 v[2:3], s[2:3]
	v_mad_i64_i32 v[4:5], s[2:3], v32, s13, v[2:3]
	v_lshl_add_u64 v[4:5], v[4:5], 0, v[20:21]
	v_lshl_add_u64 v[132:133], s[48:49], 0, v[4:5]
	v_and_b32_e32 v4, 7, v30
	v_mad_i64_i32 v[2:3], s[2:3], v31, s13, v[2:3]
	v_lshlrev_b32_e32 v4, 4, v4
	v_mov_b32_e32 v5, v1
	v_lshl_or_b32 v6, v146, 7, s4
	s_and_b32 s4, s87, 3
	v_lshl_add_u64 v[2:3], v[2:3], 0, v[4:5]
	s_lshl_b32 s14, s4, 8
	v_lshl_add_u64 v[134:135], s[48:49], 0, v[2:3]
	v_add_u32_e32 v145, v6, v7
	v_add_u32_e32 v147, v6, v8
	v_add_u32_e32 v148, v6, v9
	v_add_u32_e32 v149, v6, v10
	v_mov_b32_e32 v2, 0
	v_mov_b32_e32 v3, v150
	v_mov_b32_e32 v4, v150
	v_mov_b32_e32 v5, v150
	v_mov_b32_e32 v6, v150
	v_mov_b32_e32 v7, v150
	v_mov_b32_e32 v8, v150
	v_mov_b32_e32 v9, v150
	v_mov_b32_e32 v10, v150
	v_mov_b32_e32 v11, v150
	v_mov_b32_e32 v12, v150
	v_mov_b32_e32 v13, v150
	v_mov_b32_e32 v14, v150
	v_mov_b32_e32 v15, v150
	v_mov_b32_e32 v16, v150
	v_mov_b32_e32 v17, v150
	v_mov_b32_e32 v20, v150
	v_mov_b32_e32 v21, v150
	v_mov_b32_e32 v24, v150
	v_mov_b32_e32 v25, v150
	v_mov_b32_e32 v28, v150
	v_mov_b32_e32 v29, v150
	v_mov_b32_e32 v30, v150
	v_mov_b32_e32 v31, v150
	v_mov_b32_e32 v32, v150
	v_mov_b32_e32 v33, v150
	v_mov_b32_e32 v34, 0
	v_mov_b32_e32 v35, v150
	v_mov_b32_e32 v36, v150
	v_mov_b32_e32 v37, v150
	v_mov_b32_e32 v38, v150
	v_mov_b32_e32 v39, v150
	v_mov_b32_e32 v40, v150
	v_mov_b32_e32 v41, v150
	v_mov_b32_e32 v42, v150
	v_mov_b32_e32 v43, v150
	v_mov_b32_e32 v44, v150
	v_mov_b32_e32 v45, v150
	v_mov_b32_e32 v46, v150
	v_mov_b32_e32 v47, v150
	v_mov_b32_e32 v48, v150
	v_mov_b32_e32 v49, v150
	v_mov_b32_e32 v50, 0
	v_mov_b32_e32 v51, v150
	v_mov_b32_e32 v52, v150
	v_mov_b32_e32 v53, v150
	v_mov_b32_e32 v54, v150
	v_mov_b32_e32 v55, v150
	v_mov_b32_e32 v56, v150
	v_mov_b32_e32 v57, v150
	v_mov_b32_e32 v58, v150
	v_mov_b32_e32 v59, v150
	v_mov_b32_e32 v60, v150
	v_mov_b32_e32 v61, v150
	v_mov_b32_e32 v62, v150
	v_mov_b32_e32 v63, v150
	v_mov_b32_e32 v64, v150
	v_mov_b32_e32 v65, v150
	s_waitcnt lgkmcnt(0)
	s_barrier
; template <int DV, int NK, int MODE, bool FIXM, int GRP>
; DI void attn_job(char* lds_wg, const AttnJob& J) {
;     ...
;   bf16x8 qf[4];
;   const bf16_t* qrow = J.q + (size_t)r * UW + 8 * h;
; #pragma unroll
;   for (int ds = 0; ds < 4; ++ds) qf[ds] = *(const bf16x8*)(qrow + 16 * ds);
	v_readlane_b32 s45, v254, 34
	v_readlane_b32 s46, v254, 35
	v_readlane_b32 s47, v254, 36
	v_readlane_b32 s50, v254, 39
	v_readlane_b32 s51, v254, 40
	v_readlane_b32 s52, v254, 41
	v_readlane_b32 s53, v254, 42
	v_readlane_b32 s54, v254, 43
	v_readlane_b32 s55, v254, 44
	v_readlane_b32 s56, v254, 45
	v_readlane_b32 s57, v254, 46
	v_readlane_b32 s58, v254, 47
	v_readlane_b32 s59, v254, 48
	s_waitcnt vmcnt(4)
	v_lshlrev_b32_e32 v82, 16, v98
	v_and_b32_e32 v83, 0xffff0000, v98
	v_mul_f32_e32 v82, s7, v82
	v_mul_f32_e32 v83, s7, v83
	v_cvt_pk_bf16_f32 v98, v82, v83
	v_lshlrev_b32_e32 v82, 16, v99
	v_and_b32_e32 v83, 0xffff0000, v99
	v_mul_f32_e32 v82, s7, v82
	v_mul_f32_e32 v83, s7, v83
	v_cvt_pk_bf16_f32 v99, v82, v83
	v_lshlrev_b32_e32 v82, 16, v100
	v_and_b32_e32 v83, 0xffff0000, v100
	v_mul_f32_e32 v82, s7, v82
	v_mul_f32_e32 v83, s7, v83
	v_cvt_pk_bf16_f32 v100, v82, v83
	v_lshlrev_b32_e32 v82, 16, v101
	v_and_b32_e32 v83, 0xffff0000, v101
	v_mul_f32_e32 v82, s7, v82
	v_mul_f32_e32 v83, s7, v83
	v_cvt_pk_bf16_f32 v101, v82, v83
	v_lshlrev_b32_e32 v82, 16, v102
	v_and_b32_e32 v83, 0xffff0000, v102
	v_mul_f32_e32 v82, s7, v82
	v_mul_f32_e32 v83, s7, v83
	v_cvt_pk_bf16_f32 v102, v82, v83
	v_lshlrev_b32_e32 v82, 16, v103
	v_and_b32_e32 v83, 0xffff0000, v103
	v_mul_f32_e32 v82, s7, v82
	v_mul_f32_e32 v83, s7, v83
	v_cvt_pk_bf16_f32 v103, v82, v83
	v_lshlrev_b32_e32 v82, 16, v104
	v_and_b32_e32 v83, 0xffff0000, v104
	v_mul_f32_e32 v82, s7, v82
	v_mul_f32_e32 v83, s7, v83
	v_cvt_pk_bf16_f32 v104, v82, v83
	v_lshlrev_b32_e32 v82, 16, v105
	v_and_b32_e32 v83, 0xffff0000, v105
	v_mul_f32_e32 v82, s7, v82
	v_mul_f32_e32 v83, s7, v83
	v_cvt_pk_bf16_f32 v105, v82, v83
	v_lshlrev_b32_e32 v82, 16, v106
	v_and_b32_e32 v83, 0xffff0000, v106
	v_mul_f32_e32 v82, s7, v82
	v_mul_f32_e32 v83, s7, v83
	v_cvt_pk_bf16_f32 v106, v82, v83
	v_lshlrev_b32_e32 v82, 16, v107
	v_and_b32_e32 v83, 0xffff0000, v107
	v_mul_f32_e32 v82, s7, v82
	v_mul_f32_e32 v83, s7, v83
	v_cvt_pk_bf16_f32 v107, v82, v83
	v_lshlrev_b32_e32 v82, 16, v108
	v_and_b32_e32 v83, 0xffff0000, v108
	v_mul_f32_e32 v82, s7, v82
	v_mul_f32_e32 v83, s7, v83
	v_cvt_pk_bf16_f32 v108, v82, v83
	v_lshlrev_b32_e32 v82, 16, v109
	v_and_b32_e32 v83, 0xffff0000, v109
	v_mul_f32_e32 v82, s7, v82
	v_mul_f32_e32 v83, s7, v83
	v_cvt_pk_bf16_f32 v109, v82, v83
	v_lshlrev_b32_e32 v82, 16, v110
	v_and_b32_e32 v83, 0xffff0000, v110
	v_mul_f32_e32 v82, s7, v82
	v_mul_f32_e32 v83, s7, v83
	v_cvt_pk_bf16_f32 v110, v82, v83
	v_lshlrev_b32_e32 v82, 16, v111
	v_and_b32_e32 v83, 0xffff0000, v111
	v_mul_f32_e32 v82, s7, v82
	v_mul_f32_e32 v83, s7, v83
	v_cvt_pk_bf16_f32 v111, v82, v83
	v_lshlrev_b32_e32 v82, 16, v112
	v_and_b32_e32 v83, 0xffff0000, v112
	v_mul_f32_e32 v82, s7, v82
	v_mul_f32_e32 v83, s7, v83
	v_cvt_pk_bf16_f32 v112, v82, v83
	v_lshlrev_b32_e32 v82, 16, v113
	v_and_b32_e32 v83, 0xffff0000, v113
	v_mul_f32_e32 v82, s7, v82
	v_mul_f32_e32 v83, s7, v83
	v_cvt_pk_bf16_f32 v113, v82, v83

; template <int DV, int NK, int MODE, bool FIXM, int GRP>
; DI void attn_job(char* lds_wg, const AttnJob& J) {
;     ...
;       if (NDV == 2 || FIXM) {
;         bf16x8 ka[4], kb[4];
; #pragma unroll
;         for (int ds = 0; ds < 4; ++ds) { const int co = ((2 * ds + h) ^ ((r >> 1) & 7)) << 4; ka[ds] = *(const bf16x8*)(Kl + co); kb[ds] = *(const bf16x8*)(Kl + 4096 + co); }
; #pragma unroll
;         for (int ds = 0; ds < 4; ++ds) { sA = MFMA32(ka[ds], qf[ds], sA); sB = MFMA32(kb[ds], qf[ds], sB); }
;         __builtin_amdgcn_sched_group_barrier(0x100, 4, 0); __builtin_amdgcn_sched_group_barrier(0x008, 2, 0);
;         __builtin_amdgcn_sched_group_barrier(0x100, 2, 0); __builtin_amdgcn_sched_group_barrier(0x008, 2, 0);
;         __builtin_amdgcn_sched_group_barrier(0x100, 2, 0); __builtin_amdgcn_sched_group_barrier(0x008, 4, 0);
;       } else {
; #pragma unroll
;         for (int ds = 0; ds < 4; ++ds) {
;           const int co = ((2 * ds + h) ^ ((r >> 1) & 7)) << 4;
;           const bf16x8 ka = *(const bf16x8*)(Kl + co), kb = *(const bf16x8*)(Kl + 4096 + co);
;           sA = MFMA32(ka, qf[ds], sA); sB = MFMA32(kb, qf[ds], sB);
;         }
;       }
;       if (MODE == AM_SWA) {
;         const int qa = J.qpos0 + r, kbase = tile * 64 + 8 * h;
; #pragma unroll
;         for (int i = 0; i < 16; ++i) {
;           const int ka_ = kbase + 16 * (i >> 3) + (i & 7);
;           int d0 = qa - ka_; d0 = d0 < 0 ? -d0 : d0; if (d0 > 128) sA[i] = -INFINITY;
;           int d1 = qa - (ka_ + 32); d1 = d1 < 0 ? -d1 : d1; if (d1 > 128) sB[i] = -INFINITY;
;         }
;       }
;       if (FIXM) {
;         const float nm = -J.m_init;
; #pragma unroll
;         for (int i = 0; i < 16; ++i) { sA[i] = __builtin_amdgcn_exp2f(fmaf(sA[i], C, nm)); sB[i] = __builtin_amdgcn_exp2f(fmaf(sB[i], C, nm)); l += sA[i] + sB[i]; }
;     ...
;       if (FIXM) {
;         bf16x8 vf[4][NDV];
; #pragma unroll
;         for (int ks = 0; ks < 4; ++ks) {
; #pragma unroll
;           for (int d = 0; d < NDV; ++d) {
;             const s16x4 lo = __builtin_amdgcn_ds_read_tr16_b64_v4i16((LAS s16x4*)(Vl + ks * 2 * NDV * 512 + d * 512));
;             const s16x4 hi = __builtin_amdgcn_ds_read_tr16_b64_v4i16((LAS s16x4*)(Vl + ks * 2 * NDV * 512 + d * 512 + 256));
;             vf[ks][d] = __builtin_shufflevector(lo, hi, 0, 1, 2, 3, 4, 5, 6, 7);
;           }
;         }
; #pragma unroll
.LBB0_342:
	ds_read_b128 v[66:69], v145
	ds_read_b128 v[70:73], v145 offset:4096
	ds_read_b128 v[154:157], v147
	ds_read_b128 v[158:161], v147 offset:4096
	s_andn2_b64 vcc, exec, s[4:5]
	s_waitcnt lgkmcnt(3)
	v_mfma_f32_32x32x16_bf16 v[82:97], v[66:69], v[98:101], 0
	s_waitcnt lgkmcnt(2)
	v_mfma_f32_32x32x16_bf16 v[66:81], v[70:73], v[98:101], 0
	ds_read_b128 v[162:165], v148
	ds_read_b128 v[174:177], v148 offset:4096
	s_waitcnt lgkmcnt(3)
	v_mfma_f32_32x32x16_bf16 v[82:97], v[154:157], v[102:105], v[82:97]
	s_waitcnt lgkmcnt(2)
	v_mfma_f32_32x32x16_bf16 v[66:81], v[158:161], v[102:105], v[66:81]
	ds_read_b128 v[154:157], v149
	ds_read_b128 v[158:161], v149 offset:4096
	s_waitcnt lgkmcnt(3)
	v_mfma_f32_32x32x16_bf16 v[82:97], v[162:165], v[106:109], v[82:97]
	s_waitcnt lgkmcnt(1)
	v_mfma_f32_32x32x16_bf16 v[82:97], v[154:157], v[110:113], v[82:97]
	v_mfma_f32_32x32x16_bf16 v[66:81], v[174:177], v[106:109], v[66:81]
	s_nop 10
	v_exp_f32_e32 v153, v82
	v_exp_f32_e32 v154, v83
	v_exp_f32_e32 v155, v84
	v_exp_f32_e32 v156, v85
	s_waitcnt lgkmcnt(0)
	v_mfma_f32_32x32x16_bf16 v[66:81], v[158:161], v[110:113], v[66:81]
	v_exp_f32_e32 v158, v86
	v_exp_f32_e32 v157, v87
	v_exp_f32_e32 v159, v88
	v_exp_f32_e32 v160, v89
	ds_read_b64_tr_b16 v[86:87], v144 offset:16384
	ds_read_b64_tr_b16 v[88:89], v144 offset:16640
	ds_read_b64_tr_b16 v[174:175], v144 offset:16896
	ds_read_b64_tr_b16 v[176:177], v144 offset:17152
	ds_read_b64_tr_b16 v[178:179], v144 offset:17408
	ds_read_b64_tr_b16 v[180:181], v144 offset:17664
	ds_read_b64_tr_b16 v[182:183], v144 offset:17920
	ds_read_b64_tr_b16 v[184:185], v144 offset:18176
	v_cvt_pk_bf16_f32 v82, v153, v154
	v_cvt_pk_bf16_f32 v83, v155, v156
	v_cvt_pk_bf16_f32 v84, v158, v157
	v_cvt_pk_bf16_f32 v85, v159, v160
	ds_read_b64_tr_b16 v[186:187], v144 offset:20480
	ds_read_b64_tr_b16 v[188:189], v144 offset:20736
	ds_read_b64_tr_b16 v[190:191], v144 offset:20992
	ds_read_b64_tr_b16 v[192:193], v144 offset:21248
	ds_read_b64_tr_b16 v[194:195], v144 offset:21504
	ds_read_b64_tr_b16 v[196:197], v144 offset:21760
	ds_read_b64_tr_b16 v[198:199], v144 offset:22016
	ds_read_b64_tr_b16 v[200:201], v144 offset:22272
	s_waitcnt lgkmcnt(14)
	v_mfma_f32_32x32x16_bf16 v[50:65], v[86:89], v[82:85], v[50:65]
	v_exp_f32_e32 v168, v90
	v_exp_f32_e32 v162, v91
	v_exp_f32_e32 v163, v92
	v_exp_f32_e32 v169, v93
	s_waitcnt lgkmcnt(12)
	v_mfma_f32_32x32x16_bf16 v[34:49], v[174:177], v[82:85], v[34:49]
	v_exp_f32_e32 v164, v94
	v_exp_f32_e32 v165, v95
	v_exp_f32_e32 v170, v96
	v_exp_f32_e32 v161, v97
	s_waitcnt lgkmcnt(10)
	v_mfma_f32_32x32x16_bf16 v[18:33], v[178:181], v[82:85], v[18:33]
	v_exp_f32_e32 v176, v66
	v_exp_f32_e32 v177, v67
	v_exp_f32_e32 v178, v68
	s_waitcnt lgkmcnt(8)
	v_mfma_f32_32x32x16_bf16 v[2:17], v[182:185], v[82:85], v[2:17]
	v_cvt_pk_bf16_f32 v86, v168, v162
	v_cvt_pk_bf16_f32 v87, v163, v169
	v_cvt_pk_bf16_f32 v88, v164, v165
	v_cvt_pk_bf16_f32 v89, v170, v161
	ds_read_b64_tr_b16 v[82:83], v144 offset:24576
	ds_read_b64_tr_b16 v[84:85], v144 offset:24832
	ds_read_b64_tr_b16 v[90:91], v144 offset:25088
	ds_read_b64_tr_b16 v[92:93], v144 offset:25344
	ds_read_b64_tr_b16 v[94:95], v144 offset:25600
	ds_read_b64_tr_b16 v[96:97], v144 offset:25856
	ds_read_b64_tr_b16 v[202:203], v144 offset:26112
	ds_read_b64_tr_b16 v[204:205], v144 offset:26368
	v_exp_f32_e32 v179, v69
	s_waitcnt lgkmcnt(14)
	v_mfma_f32_32x32x16_bf16 v[50:65], v[186:189], v[86:89], v[50:65]
	v_exp_f32_e32 v180, v70
	v_exp_f32_e32 v173, v71
	v_exp_f32_e32 v174, v72
	v_exp_f32_e32 v175, v73
	s_waitcnt lgkmcnt(12)
	v_mfma_f32_32x32x16_bf16 v[34:49], v[190:193], v[86:89], v[34:49]
	v_exp_f32_e32 v186, v74
	v_exp_f32_e32 v182, v75
	v_cvt_pk_bf16_f32 v66, v176, v177
	v_cvt_pk_bf16_f32 v67, v178, v179
	s_waitcnt lgkmcnt(10)
	v_mfma_f32_32x32x16_bf16 v[18:33], v[194:197], v[86:89], v[18:33]
	v_cvt_pk_bf16_f32 v68, v180, v173
	v_cvt_pk_bf16_f32 v69, v174, v175
	v_exp_f32_e32 v183, v76
	v_exp_f32_e32 v187, v77
	v_exp_f32_e32 v184, v78
	s_waitcnt lgkmcnt(8)
	v_mfma_f32_32x32x16_bf16 v[2:17], v[198:201], v[86:89], v[2:17]
	ds_read_b64_tr_b16 v[70:71], v144 offset:28672
	ds_read_b64_tr_b16 v[72:73], v144 offset:28928
	ds_read_b64_tr_b16 v[86:87], v144 offset:29184
	ds_read_b64_tr_b16 v[88:89], v144 offset:29440
	ds_read_b64_tr_b16 v[190:191], v144 offset:29696
	ds_read_b64_tr_b16 v[192:193], v144 offset:29952
	ds_read_b64_tr_b16 v[194:195], v144 offset:30208
	ds_read_b64_tr_b16 v[196:197], v144 offset:30464
	s_waitcnt lgkmcnt(14)
	v_mfma_f32_32x32x16_bf16 v[50:65], v[82:85], v[66:69], v[50:65]
	v_exp_f32_e32 v185, v79
	v_exp_f32_e32 v188, v80
	s_waitcnt lgkmcnt(0)
	s_barrier
	v_mfma_f32_32x32x16_bf16 v[34:49], v[90:93], v[66:69], v[34:49]
	v_mfma_f32_32x32x16_bf16 v[18:33], v[94:97], v[66:69], v[18:33]
	v_mfma_f32_32x32x16_bf16 v[2:17], v[202:205], v[66:69], v[2:17]
	v_exp_f32_e32 v181, v81
	v_cvt_pk_bf16_f32 v66, v186, v182
	v_cvt_pk_bf16_f32 v67, v183, v187
	v_cvt_pk_bf16_f32 v68, v184, v185
	v_cvt_pk_bf16_f32 v69, v188, v181
	s_nop 1
	v_mfma_f32_32x32x16_bf16 v[50:65], v[70:73], v[66:69], v[50:65]
	v_mfma_f32_32x32x16_bf16 v[34:49], v[86:89], v[66:69], v[34:49]
	v_mfma_f32_32x32x16_bf16 v[18:33], v[190:193], v[66:69], v[18:33]
	v_mfma_f32_32x32x16_bf16 v[2:17], v[194:197], v[66:69], v[2:17]
	s_cbranch_vccnz .LBB0_344
	s_waitcnt vmcnt(3)
	ds_write_b128 v141, v[114:117]
	s_waitcnt vmcnt(2)
	ds_write_b128 v141, v[118:121] offset:8192
	s_waitcnt vmcnt(1)
	ds_write_b128 v151, v[122:125] offset:16384
	s_waitcnt vmcnt(0)
	ds_write_b128 v152, v[126:129] offset:16384

; template <int DV, int NK, int MODE, bool FIXM, int GRP>
; DI void attn_job(char* lds_wg, const AttnJob& J) {
;     ...
;       if (NDV == 2 || FIXM) {
;         bf16x8 ka[4], kb[4];
; #pragma unroll
;         for (int ds = 0; ds < 4; ++ds) { const int co = ((2 * ds + h) ^ ((r >> 1) & 7)) << 4; ka[ds] = *(const bf16x8*)(Kl + co); kb[ds] = *(const bf16x8*)(Kl + 4096 + co); }
; #pragma unroll
;         for (int ds = 0; ds < 4; ++ds) { sA = MFMA32(ka[ds], qf[ds], sA); sB = MFMA32(kb[ds], qf[ds], sB); }
;         __builtin_amdgcn_sched_group_barrier(0x100, 4, 0); __builtin_amdgcn_sched_group_barrier(0x008, 2, 0);
;         __builtin_amdgcn_sched_group_barrier(0x100, 2, 0); __builtin_amdgcn_sched_group_barrier(0x008, 2, 0);
;         __builtin_amdgcn_sched_group_barrier(0x100, 2, 0); __builtin_amdgcn_sched_group_barrier(0x008, 4, 0);
;       } else {
; #pragma unroll
;         for (int ds = 0; ds < 4; ++ds) {
;           const int co = ((2 * ds + h) ^ ((r >> 1) & 7)) << 4;
;           const bf16x8 ka = *(const bf16x8*)(Kl + co), kb = *(const bf16x8*)(Kl + 4096 + co);
;           sA = MFMA32(ka, qf[ds], sA); sB = MFMA32(kb, qf[ds], sB);
;         }
;       }
;       if (MODE == AM_SWA) {
;         const int qa = J.qpos0 + r, kbase = tile * 64 + 8 * h;
; #pragma unroll
;         for (int i = 0; i < 16; ++i) {
;           const int ka_ = kbase + 16 * (i >> 3) + (i & 7);
;           int d0 = qa - ka_; d0 = d0 < 0 ? -d0 : d0; if (d0 > 128) sA[i] = -INFINITY;
;           int d1 = qa - (ka_ + 32); d1 = d1 < 0 ? -d1 : d1; if (d1 > 128) sB[i] = -INFINITY;
;         }
;       }
;       if (FIXM) {
;         const float nm = -J.m_init;
; #pragma unroll
;         for (int i = 0; i < 16; ++i) { sA[i] = __builtin_amdgcn_exp2f(fmaf(sA[i], C, nm)); sB[i] = __builtin_amdgcn_exp2f(fmaf(sB[i], C, nm)); l += sA[i] + sB[i]; }
;     ...
;       bf16x8 pf[4];
;       { u32x4 w;
;         w.x = cvtpk(sA[0], sA[1]); w.y = cvtpk(sA[2], sA[3]); w.z = cvtpk(sA[4], sA[5]); w.w = cvtpk(sA[6], sA[7]); pf[0] = __builtin_bit_cast(bf16x8, w);
;         w.x = cvtpk(sA[8], sA[9]); w.y = cvtpk(sA[10], sA[11]); w.z = cvtpk(sA[12], sA[13]); w.w = cvtpk(sA[14], sA[15]); pf[1] = __builtin_bit_cast(bf16x8, w);
;         w.x = cvtpk(sB[0], sB[1]); w.y = cvtpk(sB[2], sB[3]); w.z = cvtpk(sB[4], sB[5]); w.w = cvtpk(sB[6], sB[7]); pf[2] = __builtin_bit_cast(bf16x8, w);
.LBB0_346:
	ds_read_b128 v[66:69], v145 offset:32768
	ds_read_b128 v[70:73], v145 offset:36864
	ds_read_b128 v[136:139], v147 offset:32768
	ds_read_b128 v[190:193], v147 offset:36864
	v_lshl_add_u64 v[132:133], v[132:133], 0, s[94:95]
	v_lshl_add_u64 v[134:135], v[134:135], 0, s[94:95]
	s_and_b64 vcc, exec, s[2:3]
	s_waitcnt lgkmcnt(3)
	v_mfma_f32_32x32x16_bf16 v[82:97], v[66:69], v[98:101], 0
	s_waitcnt lgkmcnt(2)
	v_mfma_f32_32x32x16_bf16 v[66:81], v[70:73], v[98:101], 0
	ds_read_b128 v[194:197], v148 offset:32768
	ds_read_b128 v[198:201], v148 offset:36864
	s_waitcnt lgkmcnt(3)
	v_mfma_f32_32x32x16_bf16 v[82:97], v[136:139], v[102:105], v[82:97]
	v_add_f32_e32 v136, v153, v176
	v_add_f32_e32 v136, v150, v136
	v_add_f32_e32 v137, v154, v177
	v_add_f32_e32 v136, v137, v136
	v_add_f32_e32 v137, v155, v178
	v_add_f32_e32 v136, v137, v136
	v_add_f32_e32 v137, v156, v179
	s_waitcnt lgkmcnt(2)
	v_mfma_f32_32x32x16_bf16 v[66:81], v[190:193], v[102:105], v[66:81]
	v_add_f32_e32 v136, v137, v136
	v_add_f32_e32 v137, v158, v180
	v_add_f32_e32 v154, v137, v136
	ds_read_b128 v[136:139], v149 offset:32768
	ds_read_b128 v[150:153], v149 offset:36864
	v_add_f32_e32 v155, v157, v173
	v_add_f32_e32 v154, v155, v154
	s_waitcnt lgkmcnt(3)
	v_mfma_f32_32x32x16_bf16 v[82:97], v[194:197], v[106:109], v[82:97]
	v_add_f32_e32 v155, v159, v174
	v_add_f32_e32 v154, v155, v154
	v_add_f32_e32 v155, v160, v175
	v_add_f32_e32 v154, v155, v154
	v_add_f32_e32 v155, v168, v186
	v_add_f32_e32 v154, v155, v154
	v_add_f32_e32 v155, v162, v182
	s_waitcnt lgkmcnt(2)
	v_mfma_f32_32x32x16_bf16 v[66:81], v[198:201], v[106:109], v[66:81]
	v_add_f32_e32 v154, v155, v154
	v_add_f32_e32 v155, v163, v183
	v_add_f32_e32 v154, v155, v154
	v_add_f32_e32 v155, v169, v187
	v_add_f32_e32 v154, v155, v154
	s_waitcnt lgkmcnt(1)
	v_mfma_f32_32x32x16_bf16 v[82:97], v[136:139], v[110:113], v[82:97]
	v_add_f32_e32 v136, v164, v184
	v_add_f32_e32 v136, v136, v154
	v_add_f32_e32 v137, v165, v185
	v_add_f32_e32 v136, v137, v136
	v_add_f32_e32 v137, v170, v188
	s_nop 6
	s_waitcnt lgkmcnt(0)
	v_mfma_f32_32x32x16_bf16 v[66:81], v[150:153], v[110:113], v[66:81]
	v_exp_f32_e32 v82, v82
	v_exp_f32_e32 v83, v83
	ds_read_b64_tr_b16 v[138:139], v144 offset:50432
	ds_read_b64_tr_b16 v[150:151], v144 offset:50688
	ds_read_b64_tr_b16 v[152:153], v144 offset:50944
	ds_read_b64_tr_b16 v[154:155], v144 offset:53248
	s_nop 4
	v_exp_f32_e32 v170, v66
	v_exp_f32_e32 v173, v67
	v_add_f32_e32 v66, v137, v136
	v_add_f32_e32 v136, v161, v181
	v_exp_f32_e32 v67, v84
	v_exp_f32_e32 v181, v68
	v_add_f32_e32 v66, v136, v66
	v_add_f32_e32 v136, v82, v170
	v_add_f32_e32 v66, v66, v136
	v_add_f32_e32 v68, v83, v173
	v_add_f32_e32 v66, v68, v66
	v_add_f32_e32 v68, v67, v181
	v_add_f32_e32 v169, v68, v66
	v_exp_f32_e32 v179, v85
	v_exp_f32_e32 v183, v69
	v_exp_f32_e32 v185, v86
	v_exp_f32_e32 v187, v70
	v_exp_f32_e32 v70, v87
	v_exp_f32_e32 v188, v88
	v_exp_f32_e32 v168, v89
	v_cvt_pk_bf16_f32 v66, v82, v83
	ds_read_b64_tr_b16 v[82:83], v144 offset:49152
	ds_read_b64_tr_b16 v[84:85], v144 offset:49408
	v_exp_f32_e32 v178, v71
	ds_read_b64_tr_b16 v[86:87], v144 offset:49664
	ds_read_b64_tr_b16 v[88:89], v144 offset:49920
	v_exp_f32_e32 v189, v90
	ds_read_b64_tr_b16 v[136:137], v144 offset:50176
	v_exp_f32_e32 v180, v91
	v_exp_f32_e32 v190, v92
	v_exp_f32_e32 v182, v93
	v_exp_f32_e32 v191, v94
	v_exp_f32_e32 v184, v95
	v_cvt_pk_bf16_f32 v67, v67, v179
	v_cvt_pk_bf16_f32 v68, v185, v70
	v_cvt_pk_bf16_f32 v69, v188, v168
	ds_read_b64_tr_b16 v[156:157], v144 offset:53504
	v_exp_f32_e32 v192, v96
	ds_read_b64_tr_b16 v[158:159], v144 offset:53760
	ds_read_b64_tr_b16 v[160:161], v144 offset:54016
	ds_read_b64_tr_b16 v[162:163], v144 offset:54272
	ds_read_b64_tr_b16 v[164:165], v144 offset:54528
	ds_read_b64_tr_b16 v[174:175], v144 offset:54784
	ds_read_b64_tr_b16 v[176:177], v144 offset:55040
	s_waitcnt lgkmcnt(10)
	v_mfma_f32_32x32x16_bf16 v[50:65], v[82:85], v[66:69], v[50:65]
	v_exp_f32_e32 v186, v97
	v_add_f32_e32 v71, v179, v183
	v_add_f32_e32 v179, v71, v169
	v_add_f32_e32 v71, v185, v187
	v_pk_add_f32 v[70:71], v[70:71], v[178:179]
	v_cvt_pk_bf16_f32 v82, v189, v180
	v_cvt_pk_bf16_f32 v83, v190, v182
	s_waitcnt lgkmcnt(8)
	v_mfma_f32_32x32x16_bf16 v[34:49], v[86:89], v[66:69], v[34:49]
	v_cvt_pk_bf16_f32 v84, v191, v184
	v_cvt_pk_bf16_f32 v85, v192, v186
	s_waitcnt lgkmcnt(7)
	v_mfma_f32_32x32x16_bf16 v[18:33], v[136:139], v[66:69], v[18:33]
	v_add_f32_e64 v136, v70, v70
	v_add_f32_e64 v137, v70, v71
	v_exp_f32_e32 v138, v72
	v_exp_f32_e32 v136, v73
	v_cvt_pk_bf16_f32 v72, v187, v178
	v_add_f32_e32 v169, v188, v138
	v_mfma_f32_32x32x16_bf16 v[2:17], v[150:153], v[66:69], v[2:17]
	ds_read_b64_tr_b16 v[66:67], v144 offset:57344
	ds_read_b64_tr_b16 v[68:69], v144 offset:57600
	ds_read_b64_tr_b16 v[86:87], v144 offset:57856
	ds_read_b64_tr_b16 v[88:89], v144 offset:58112
	ds_read_b64_tr_b16 v[90:91], v144 offset:58368
	ds_read_b64_tr_b16 v[92:93], v144 offset:58624
	ds_read_b64_tr_b16 v[94:95], v144 offset:58880
	ds_read_b64_tr_b16 v[96:97], v144 offset:59136
	s_waitcnt lgkmcnt(14)
	v_mfma_f32_32x32x16_bf16 v[50:65], v[154:157], v[82:85], v[50:65]
	v_add_f32_e64 v70, v168, v136
	v_add_f32_e64 v71, v169, v137
	v_cvt_pk_bf16_f32 v73, v138, v136
	s_waitcnt lgkmcnt(12)
	v_mfma_f32_32x32x16_bf16 v[34:49], v[158:161], v[82:85], v[34:49]
	v_add_f32_e64 v158, v70, v70
	v_add_f32_e64 v159, v70, v71
	v_exp_f32_e32 v160, v74
	v_exp_f32_e32 v158, v75
	v_cvt_pk_bf16_f32 v70, v170, v173
	v_cvt_pk_bf16_f32 v71, v181, v183
	v_add_f32_e32 v181, v189, v160
	s_waitcnt lgkmcnt(10)
	v_mfma_f32_32x32x16_bf16 v[18:33], v[162:165], v[82:85], v[18:33]
	s_waitcnt lgkmcnt(8)
	v_mfma_f32_32x32x16_bf16 v[2:17], v[174:177], v[82:85], v[2:17]
	ds_read_b64_tr_b16 v[82:83], v144 offset:61440
	ds_read_b64_tr_b16 v[84:85], v144 offset:61696
	ds_read_b64_tr_b16 v[136:137], v144 offset:61952
	ds_read_b64_tr_b16 v[138:139], v144 offset:62208
	ds_read_b64_tr_b16 v[150:151], v144 offset:62464
	ds_read_b64_tr_b16 v[152:153], v144 offset:62720
	ds_read_b64_tr_b16 v[154:155], v144 offset:62976
	ds_read_b64_tr_b16 v[156:157], v144 offset:63232
	s_waitcnt lgkmcnt(14)
	v_mfma_f32_32x32x16_bf16 v[50:65], v[66:69], v[70:73], v[50:65]
	v_add_f32_e64 v66, v180, v158
	v_add_f32_e64 v67, v181, v159
	s_waitcnt lgkmcnt(0)
	v_add_f32_e64 v68, v66, v66
	v_add_f32_e64 v69, v66, v67
	v_exp_f32_e32 v159, v76
	v_exp_f32_e32 v68, v77
	v_mfma_f32_32x32x16_bf16 v[34:49], v[86:89], v[70:73], v[34:49]
	v_add_f32_e32 v183, v190, v159
	s_barrier
; #define LAS __attribute__((address_space(3)))
; template <int DV, int NK, int MODE, bool FIXM, int GRP>
; DI void attn_job(char* lds_wg, const AttnJob& J) {
;     ...
;         for (int i = 0; i < 16; ++i) { sA[i] = __builtin_amdgcn_exp2f(fmaf(sA[i], C, nm)); sB[i] = __builtin_amdgcn_exp2f(fmaf(sB[i], C, nm)); l += sA[i] + sB[i]; }
;       } else {
;       float mx = sA[0];
; #pragma unroll
;       for (int i = 1; i < 16; ++i) mx = fmaxf(mx, sA[i]);
; #pragma unroll
;       for (int i = 0; i < 16; ++i) mx = fmaxf(mx, sB[i]);
;       mx = swapmax(mx);
;       const float mn = fmaxf(m, mx * C);
;       const float alpha = __builtin_amdgcn_exp2f(m - mn);
;       m = mn;
;       float ps = 0.f;
; #pragma unroll
;       for (int i = 0; i < 16; ++i) { sA[i] = __builtin_amdgcn_exp2f(fmaf(sA[i], C, -mn)); sB[i] = __builtin_amdgcn_exp2f(fmaf(sB[i], C, -mn)); ps += sA[i] + sB[i]; }
;       l = l * alpha + ps;
; #pragma unroll
;       for (int d = 0; d < NDV; ++d)
; #pragma unroll
;         for (int i = 0; i < 16; ++i) O[d][i] *= alpha;
;       }
;       bf16x8 pf[4];
;       { u32x4 w;
;         w.x = cvtpk(sA[0], sA[1]); w.y = cvtpk(sA[2], sA[3]); w.z = cvtpk(sA[4], sA[5]); w.w = cvtpk(sA[6], sA[7]); pf[0] = __builtin_bit_cast(bf16x8, w);
;         w.x = cvtpk(sA[8], sA[9]); w.y = cvtpk(sA[10], sA[11]); w.z = cvtpk(sA[12], sA[13]); w.w = cvtpk(sA[14], sA[15]); pf[1] = __builtin_bit_cast(bf16x8, w);
;         w.x = cvtpk(sB[0], sB[1]); w.y = cvtpk(sB[2], sB[3]); w.z = cvtpk(sB[4], sB[5]); w.w = cvtpk(sB[6], sB[7]); pf[2] = __builtin_bit_cast(bf16x8, w);
;         w.x = cvtpk(sB[8], sB[9]); w.y = cvtpk(sB[10], sB[11]); w.z = cvtpk(sB[12], sB[13]); w.w = cvtpk(sB[14], sB[15]); pf[3] = __builtin_bit_cast(bf16x8, w); }
;       const char* Vl = lds + stage * 32768 + NK * 8192 + vrd;
;       if (FIXM) {
;         bf16x8 vf[4][NDV];
; #pragma unroll
;         for (int ks = 0; ks < 4; ++ks) {
; #pragma unroll
;           for (int d = 0; d < NDV; ++d) {
;             const s16x4 lo = __builtin_amdgcn_ds_read_tr16_b64_v4i16((LAS s16x4*)(Vl + ks * 2 * NDV * 512 + d * 512));
;             const s16x4 hi = __builtin_amdgcn_ds_read_tr16_b64_v4i16((LAS s16x4*)(Vl + ks * 2 * NDV * 512 + d * 512 + 256));
;             vf[ks][d] = __builtin_shufflevector(lo, hi, 0, 1, 2, 3, 4, 5, 6, 7);
;           }
;         }
; #pragma unroll
;         for (int ks = 0; ks < 4; ++ks) {
; #pragma unroll
	v_add_f32_e64 v66, v182, v68
	v_add_f32_e64 v67, v183, v69
	v_add_f32_e64 v74, v66, v66
	v_add_f32_e64 v75, v66, v67
	v_exp_f32_e32 v69, v78
	v_exp_f32_e32 v74, v79
	v_mfma_f32_32x32x16_bf16 v[18:33], v[90:93], v[70:73], v[18:33]
	v_add_f32_e32 v185, v191, v69
	v_add_f32_e64 v66, v184, v74
	v_add_f32_e64 v67, v185, v75
	v_add_f32_e64 v76, v66, v66
	v_add_f32_e64 v77, v66, v67
	v_cvt_pk_bf16_f32 v67, v159, v68
	v_cvt_pk_bf16_f32 v68, v69, v74
	v_mfma_f32_32x32x16_bf16 v[2:17], v[94:97], v[70:73], v[2:17]
	v_exp_f32_e32 v70, v80
	v_exp_f32_e32 v76, v81
	v_cvt_pk_bf16_f32 v66, v160, v158
	v_add_f32_e32 v187, v192, v70
	v_cvt_pk_bf16_f32 v69, v70, v76
	v_pk_add_f32 v[70:71], v[186:187], v[76:77]
	s_nop 0
	v_mfma_f32_32x32x16_bf16 v[50:65], v[82:85], v[66:69], v[50:65]
	v_mfma_f32_32x32x16_bf16 v[34:49], v[136:139], v[66:69], v[34:49]
	v_mfma_f32_32x32x16_bf16 v[18:33], v[150:153], v[66:69], v[18:33]
	v_add_f32_e32 v150, v70, v71
	v_mfma_f32_32x32x16_bf16 v[2:17], v[154:157], v[66:69], v[2:17]
	s_cbranch_vccnz .LBB0_348
	s_mov_b32 s41, s40
	s_branch .LBB0_340
